# v32 + tile-pointer SALU ladder hoisted above the per-tile barrier in the 8 live attention loops (7.11 rotation)
# speedup vs baseline: 1.0078x; 1.0078x over previous
; DEVI void attn_item(const Params& p, int bg, int t0, unsigned char* smem) {
;     ...
;     auto tile_ptrs = [&](int n, const bf16_t*& kp, const bf16_t*& vp) {
;         if (n < n2) { const int c = n < n1 ? n : n - n1; kp = kc + (size_t)c * 4096; vp = vct + (size_t)c * 4096; }
;         else if (n < n3) { const int j = n - n2; kp = ksl + (size_t)j * 4096; vp = vsl + (size_t)j * 4096; }
;         else { const int j = jlo + (n - n3); kp = kwn + (size_t)j * 4096; vp = vwn + (size_t)j * 4096; }
;     ...
;     auto body = [&](auto kc, const int n) {
;         constexpr int KIND = decltype(kc)::value;
;         asm volatile("s_waitcnt vmcnt(0)\n\ts_barrier" ::: "memory");
;         if (n + 1 < ntot) {
;             const bf16_t *kp, *vp; tile_ptrs(n + 1, kp, vp);
;             glds_tile4(gv0, gv1, kp, vp, __builtin_amdgcn_readfirstlane(alds0 + ((n + 1) & 1) * 16384));
.LBB0_408:
	s_add_i32 s91, s93, 1
	s_cmp_lt_i32 s91, s22
	s_mov_b64 s[14:15], -1
	s_cbranch_scc1 .LBB0_410
	s_add_i32 s40, s92, 0x4000
	s_mov_b64 s[14:15], 0

; DEVI void attn_item(const Params& p, int bg, int t0, unsigned char* smem) {
;     ...
;         asm volatile("s_waitcnt vmcnt(0)\n\ts_barrier" ::: "memory");
;         if (n + 1 < ntot) {
;             const bf16_t *kp, *vp; tile_ptrs(n + 1, kp, vp);
;             glds_tile4(gv0, gv1, kp, vp, __builtin_amdgcn_readfirstlane(alds0 + ((n + 1) & 1) * 16384));
;         }
;         const unsigned char* cK = smem + (n & 1) * 16384;
;         const unsigned char* cV = cK + 8192;
;         constexpr bool is_p1 = KIND == 0, is_p2 = KIND == 1, is_slc = KIND == 2 || KIND == 4;
;         const int jt = is_slc ? n - n2 : jlo + (n - n3);
;         constexpr bool elem = KIND == 3 || KIND == 4;
;         const int wlim = is_slc ? 0x40000000 : 512;
;         const int c0 = (is_p1 ? n : n - n1) * 64;
;         bool any_act = true;
;         if (is_slc && !elem) {
;             const unsigned aw = __builtin_amdgcn_readfirstlane(anyw[jt >> 5] | anyw[4 + (jt >> 5)]);
;             any_act = (aw >> (jt & 31)) & 1u;
;         }
;         if (any_act) {
;             f32x4 s[2][4];
;             {
;                 bf16x8 k0[4], k1[4];
; #pragma unroll
;                 for (int mt = 0; mt < 4; ++mt) {
;                     k0[mt] = *(const bf16x8*)(cK + (mt * 16 + l16) * 128 + ((quad ^ rsw) * 16));
;                     k1[mt] = *(const bf16x8*)(cK + (mt * 16 + l16) * 128 + (((4 + quad) ^ rsw) * 16));
;                 }
; #pragma unroll
;                 for (int mt = 0; mt < 4; ++mt)
; #pragma unroll
;                     for (int ct = 0; ct < 2; ++ct) s[ct][mt] = mfma16(k0[mt], qf[ct][0], (f32x4){0.f, 0.f, 0.f, 0.f});
; #pragma unroll
;                 for (int mt = 0; mt < 4; ++mt)
; #pragma unroll
;                     for (int ct = 0; ct < 2; ++ct) s[ct][mt] = mfma16(k1[mt], qf[ct][1], s[ct][mt]);
;             }
;             if (is_p1) {
;                 float bm[2];
; #pragma unroll
;                 for (int ct = 0; ct < 2; ++ct) {
;                     bm[ct] = NINF;
; #pragma unroll
;                     for (int mt = 0; mt < 4; ++mt)
; #pragma unroll
;                         for (int rr = 0; rr < 4; ++rr) {
;                             const int c = c0 + mt * 16 + quad * 4 + rr;
;                             const float x = (16 * c + 31 <= tq[ct]) ? s[ct][mt][rr] * LOG2E : NINF;
;                             s[ct][mt][rr] = x; bm[ct] = fmaxf(bm[ct], x);
.LBB0_419:
	s_ashr_i32 s15, s14, 31
	s_lshl_b64 s[14:15], s[14:15], 13
	s_add_u32 s68, s68, s14
	s_addc_u32 s69, s69, s15
	s_add_u32 s14, s40, s14
	s_addc_u32 s15, s41, s15
	s_add_i32 s40, s92, 0x4000
	s_and_b32 s41, s40, 0x4000
	s_add_i32 s41, s41, s82
	s_waitcnt vmcnt(0)
	s_barrier
	s_mov_b32 s70, m0
	s_mov_b32 m0, s41
	s_nop 0
	global_load_lds_dwordx4 v158, s[68:69]
	s_add_u32 m0, m0, 0x1000
	s_nop 0
	global_load_lds_dwordx4 v159, s[68:69]
	s_add_u32 m0, m0, 0x1000
	s_nop 0
	global_load_lds_dwordx4 v158, s[14:15]
	s_add_u32 m0, m0, 0x1000
	s_nop 0
	global_load_lds_dwordx4 v159, s[14:15]
	s_mov_b32 m0, s70
	s_branch .LBB0_420
.Lawb_a:
	s_waitcnt vmcnt(0)
	s_barrier
.LBB0_420:
	s_and_b32 s14, s92, 0x4000
	v_or_b32_e32 v28, s14, v160
	v_add_u32_e32 v48, v28, v161
	ds_read_b128 v[24:27], v48
	v_add_u32_e32 v52, v28, v162
	ds_read_b128 v[28:31], v52
	ds_read_b128 v[32:35], v48 offset:2048
	ds_read_b128 v[36:39], v52 offset:2048
	ds_read_b128 v[40:43], v48 offset:4096
	ds_read_b128 v[44:47], v52 offset:4096
	ds_read_b128 v[48:51], v48 offset:6144
	ds_read_b128 v[52:55], v52 offset:6144
	s_waitcnt vmcnt(5) lgkmcnt(5)
	v_mfma_f32_16x16x32_bf16 v[60:63], v[32:35], v[4:7], 0
	s_cmp_lg_u32 s89, s91
	s_waitcnt vmcnt(2)
	v_mfma_f32_16x16x32_bf16 v[32:35], v[32:35], v[12:15], 0
	v_mfma_f32_16x16x32_bf16 v[56:59], v[24:27], v[4:7], 0
	v_mfma_f32_16x16x32_bf16 v[24:27], v[24:27], v[12:15], 0
	s_waitcnt lgkmcnt(3)
	v_mfma_f32_16x16x32_bf16 v[64:67], v[40:43], v[4:7], 0
	v_mfma_f32_16x16x32_bf16 v[40:43], v[40:43], v[12:15], 0
	s_waitcnt lgkmcnt(1)
	v_mfma_f32_16x16x32_bf16 v[68:71], v[48:51], v[4:7], 0
	v_mfma_f32_16x16x32_bf16 v[48:51], v[48:51], v[12:15], 0
	v_mfma_f32_16x16x32_bf16 v[56:59], v[28:31], v[8:11], v[56:59]
	s_waitcnt vmcnt(1)
	v_mfma_f32_16x16x32_bf16 v[24:27], v[28:31], v[16:19], v[24:27]
	v_mfma_f32_16x16x32_bf16 v[28:31], v[36:39], v[8:11], v[60:63]
	s_nop 4
	v_mul_f32_e32 v58, 0x3fb8aa3b, v58
	v_mul_f32_e32 v59, 0x3fb8aa3b, v59
	v_mul_f32_e32 v24, 0x3fb8aa3b, v24
	v_mfma_f32_16x16x32_bf16 v[32:35], v[36:39], v[16:19], v[32:35]
	v_add_u32_e32 v60, 0xfffffcf0, v2
	v_add_u32_e32 v61, 0xfffffd00, v2
	v_add_u32_e32 v62, 0xfffffdd0, v2
	v_mfma_f32_16x16x32_bf16 v[36:39], v[44:47], v[8:11], v[64:67]
	v_mul_f32_e32 v28, 0x3fb8aa3b, v28
	v_mul_f32_e32 v29, 0x3fb8aa3b, v29
	v_mul_f32_e32 v30, 0x3fb8aa3b, v30
	v_mfma_f32_16x16x32_bf16 v[40:43], v[44:47], v[16:19], v[40:43]
	v_add_u32_e32 v64, 0xfffffdf0, v2
	v_mul_f32_e32 v31, 0x3fb8aa3b, v31
	v_add_u32_e32 v66, 0xfffffed0, v2
	s_waitcnt lgkmcnt(0)
	v_mfma_f32_16x16x32_bf16 v[44:47], v[52:55], v[8:11], v[68:71]
	v_mul_f32_e32 v36, 0x3fb8aa3b, v36
	v_mul_f32_e32 v37, 0x3fb8aa3b, v37
	v_mul_f32_e32 v38, 0x3fb8aa3b, v38
	v_mfma_f32_16x16x32_bf16 v[48:51], v[52:55], v[16:19], v[48:51]
	v_add_u32_e32 v53, 0xfffffcd0, v2
	v_mul_f32_e32 v54, 0x3fb8aa3b, v56
	v_cmp_le_i32_e32 vcc, v53, v126
	v_add_u32_e32 v55, 0xfffffce0, v2
	v_mul_f32_e32 v56, 0x3fb8aa3b, v57
	v_cndmask_b32_e32 v54, v147, v54, vcc
	v_cmp_le_i32_e32 vcc, v55, v126
	v_add_u32_e32 v68, 0xfffffef0, v2
	v_subrev_u32_e32 v52, 48, v2
	v_cndmask_b32_e32 v56, v147, v56, vcc
	v_cmp_le_i32_e32 vcc, v60, v126
	v_mul_f32_e32 v39, 0x3fb8aa3b, v39
	v_mul_f32_e32 v44, 0x3fb8aa3b, v44
	v_cndmask_b32_e32 v58, v147, v58, vcc
	v_cmp_le_i32_e32 vcc, v61, v126
	v_max3_f32 v57, v54, s78, v56
	v_mul_f32_e32 v45, 0x3fb8aa3b, v45
	v_cndmask_b32_e32 v59, v147, v59, vcc
	v_cmp_le_i32_e32 vcc, v62, v126
	v_add_u32_e32 v71, -16, v2
	v_max3_f32 v57, v57, v58, v59
	v_cndmask_b32_e32 v63, v147, v28, vcc
	v_add_u32_e32 v28, 0xfffffde0, v2
	v_cmp_le_i32_e32 vcc, v28, v126
	v_mul_f32_e32 v46, 0x3fb8aa3b, v46
	v_mul_f32_e32 v26, 0x3fb8aa3b, v26
	v_cndmask_b32_e32 v29, v147, v29, vcc
	v_cmp_le_i32_e32 vcc, v64, v126
	v_max3_f32 v57, v57, v63, v29
	s_nop 0
	v_cndmask_b32_e32 v65, v147, v30, vcc
	v_add_u32_e32 v30, 0xfffffe00, v2
	v_cmp_le_i32_e32 vcc, v30, v126
	s_nop 1
	v_cndmask_b32_e32 v31, v147, v31, vcc
	v_cmp_le_i32_e32 vcc, v66, v126
	v_max3_f32 v57, v57, v65, v31
	s_nop 0
	v_cndmask_b32_e32 v67, v147, v36, vcc
	v_add_u32_e32 v36, 0xfffffee0, v2
	v_cmp_le_i32_e32 vcc, v36, v126
	s_nop 1
	v_cndmask_b32_e32 v37, v147, v37, vcc
	v_cmp_le_i32_e32 vcc, v68, v126
	v_max3_f32 v57, v57, v67, v37
	s_nop 0
	v_cndmask_b32_e32 v69, v147, v38, vcc
	v_add_u32_e32 v38, 0xffffff00, v2
	v_cmp_le_i32_e32 vcc, v38, v126
	s_nop 1
	v_cndmask_b32_e32 v39, v147, v39, vcc
	v_cmp_le_i32_e32 vcc, v52, v126
	v_max3_f32 v57, v57, v69, v39
	s_nop 0
	v_cndmask_b32_e32 v70, v147, v44, vcc
	v_subrev_u32_e32 v44, 32, v2
	v_cmp_le_i32_e32 vcc, v44, v126
	s_nop 1
	v_cndmask_b32_e32 v45, v147, v45, vcc
	v_cmp_le_i32_e32 vcc, v71, v126
	v_max3_f32 v57, v57, v70, v45
	s_nop 0
	v_cndmask_b32_e32 v72, v147, v46, vcc
	v_mul_f32_e32 v46, 0x3fb8aa3b, v47
	v_cmp_le_i32_e32 vcc, v2, v126
	s_nop 1
	v_cndmask_b32_e32 v47, v147, v46, vcc
	v_cmp_le_i32_e32 vcc, v53, v124
	v_max3_f32 v46, v57, v72, v47
	s_nop 0
	v_cndmask_b32_e32 v53, v147, v24, vcc
	v_mul_f32_e32 v24, 0x3fb8aa3b, v25
	v_cmp_le_i32_e32 vcc, v55, v124
	s_nop 1
	v_cndmask_b32_e32 v25, v147, v24, vcc
; DEVI float fast_exp2(float x) { return __builtin_amdgcn_exp2f(x); }
; DEVI float rmax16(float x) { const unsigned u = __float_as_uint(x); const auto r = __builtin_amdgcn_permlane16_swap(u, u, false, false); return fmaxf(__uint_as_float(r[0]), __uint_as_float(r[1])); }
; DEVI float rmax32(float x) { const unsigned u = __float_as_uint(x); const auto r = __builtin_amdgcn_permlane32_swap(u, u, false, false); return fmaxf(__uint_as_float(r[0]), __uint_as_float(r[1])); }
; DEVI void attn_item(const Params& p, int bg, int t0, unsigned char* smem) {
;     ...
;                             const int c = c0 + mt * 16 + quad * 4 + rr;
;                             const float x = (16 * c + 31 <= tq[ct]) ? s[ct][mt][rr] * LOG2E : NINF;
;                             s[ct][mt][rr] = x; bm[ct] = fmaxf(bm[ct], x);
;                         }
;                 }
; #pragma unroll
;                 for (int ct = 0; ct < 2; ++ct) bm[ct] = rmax16(bm[ct]);
; #pragma unroll
;                 for (int ct = 0; ct < 2; ++ct) bm[ct] = rmax32(bm[ct]);
; #pragma unroll
;                 for (int ct = 0; ct < 2; ++ct) {
;                     const float mn = fmaxf(m[ct], bm[ct]);
;                     float ls = 0.f;
; #pragma unroll
;                     for (int mt = 0; mt < 4; ++mt)
; #pragma unroll
;                         for (int rr = 0; rr < 4; ++rr) ls += fast_exp2(s[ct][mt][rr] - mn);
;                     lsum[ct] = lsum[ct] * fast_exp2(m[ct] - mn) + ls;
;                     m[ct] = mn;
;                 }
	v_cmp_le_i32_e32 vcc, v60, v124
	v_max3_f32 v24, v53, s78, v25
	s_nop 0
	v_cndmask_b32_e32 v55, v147, v26, vcc
	v_mul_f32_e32 v26, 0x3fb8aa3b, v27
	v_cmp_le_i32_e32 vcc, v61, v124
	s_nop 1
	v_cndmask_b32_e32 v57, v147, v26, vcc
	v_mul_f32_e32 v26, 0x3fb8aa3b, v32
	v_cmp_le_i32_e32 vcc, v62, v124
	v_max3_f32 v24, v24, v55, v57
	s_nop 0
	v_cndmask_b32_e32 v60, v147, v26, vcc
	v_mul_f32_e32 v26, 0x3fb8aa3b, v33
	v_cmp_le_i32_e32 vcc, v28, v124
	s_nop 1
	v_cndmask_b32_e32 v61, v147, v26, vcc
	v_mul_f32_e32 v26, 0x3fb8aa3b, v34
	v_cmp_le_i32_e32 vcc, v64, v124
	v_max3_f32 v24, v24, v60, v61
	s_nop 0
	v_cndmask_b32_e32 v62, v147, v26, vcc
	v_mul_f32_e32 v26, 0x3fb8aa3b, v35
	v_cmp_le_i32_e32 vcc, v30, v124
	s_nop 1
	v_cndmask_b32_e32 v64, v147, v26, vcc
	v_mul_f32_e32 v26, 0x3fb8aa3b, v40
	v_cmp_le_i32_e32 vcc, v66, v124
	v_max3_f32 v24, v24, v62, v64
	s_nop 0
	v_cndmask_b32_e32 v66, v147, v26, vcc
	v_mul_f32_e32 v26, 0x3fb8aa3b, v41
	v_cmp_le_i32_e32 vcc, v36, v124
	s_nop 1
	v_cndmask_b32_e32 v73, v147, v26, vcc
	v_mul_f32_e32 v26, 0x3fb8aa3b, v42
	v_cmp_le_i32_e32 vcc, v68, v124
	v_max3_f32 v24, v24, v66, v73
	s_nop 0
	v_cndmask_b32_e32 v68, v147, v26, vcc
	v_mul_f32_e32 v26, 0x3fb8aa3b, v43
	v_cmp_le_i32_e32 vcc, v38, v124
	s_nop 1
	v_cndmask_b32_e32 v74, v147, v26, vcc
	v_mul_f32_e32 v26, 0x3fb8aa3b, v48
	v_cmp_le_i32_e32 vcc, v52, v124
	v_max3_f32 v24, v24, v68, v74
	s_nop 0
	v_cndmask_b32_e32 v75, v147, v26, vcc
	v_mul_f32_e32 v26, 0x3fb8aa3b, v49
	v_cmp_le_i32_e32 vcc, v44, v124
	s_nop 1
	v_cndmask_b32_e32 v76, v147, v26, vcc
	v_mul_f32_e32 v26, 0x3fb8aa3b, v50
	v_cmp_le_i32_e32 vcc, v71, v124
	v_max3_f32 v24, v24, v75, v76
	s_nop 0
	v_cndmask_b32_e32 v71, v147, v26, vcc
	v_mul_f32_e32 v26, 0x3fb8aa3b, v51
	v_cmp_le_i32_e32 vcc, v2, v124
	v_add_u32_e32 v2, 0x400, v2
	s_nop 0
	v_cndmask_b32_e32 v77, v147, v26, vcc
	v_mov_b32_e32 v26, v46
	s_nop 1
	v_permlane16_swap_b32_e32 v46, v26
	v_max3_f32 v24, v24, v71, v77
	v_max_f32_e32 v26, v26, v26
	v_max_f32_e32 v27, v46, v46
	v_max_f32_e32 v26, v27, v26
	v_mov_b32_e32 v27, v24
	s_nop 1
	v_permlane16_swap_b32_e32 v24, v27
	v_max_f32_e32 v27, v27, v27
	v_max_f32_e32 v24, v24, v24
	v_max_f32_e32 v27, v24, v27
	v_mov_b32_e32 v24, v26
	s_nop 1
	v_permlane32_swap_b32_e32 v26, v24
	v_max3_f32 v24, v23, v26, v24
	v_sub_f32_e32 v29, v29, v24
	v_exp_f32_e32 v36, v29
	v_sub_f32_e32 v29, v65, v24
	v_exp_f32_e32 v38, v29
	v_sub_f32_e32 v29, v31, v24
	v_exp_f32_e32 v40, v29
	v_sub_f32_e32 v29, v67, v24
	v_exp_f32_e32 v42, v29
	v_sub_f32_e32 v29, v37, v24
	v_exp_f32_e32 v44, v29
	v_sub_f32_e32 v29, v69, v24
	v_mov_b32_e32 v33, v27
	v_exp_f32_e32 v46, v29
	v_sub_f32_e32 v29, v39, v24
	v_permlane32_swap_b32_e32 v27, v33
	v_exp_f32_e32 v48, v29
	v_sub_f32_e32 v29, v70, v24
	v_sub_f32_e32 v23, v23, v24
	v_sub_f32_e32 v30, v58, v24
	v_exp_f32_e32 v50, v29
	v_sub_f32_e32 v29, v45, v24
	v_exp_f32_e32 v58, v23
	v_max3_f32 v23, v22, v27, v33
	v_sub_f32_e32 v26, v54, v24
	v_exp_f32_e32 v52, v29
	v_sub_f32_e32 v29, v72, v24
	v_sub_f32_e32 v27, v53, v23
	v_exp_f32_e32 v26, v26
	v_sub_f32_e32 v28, v56, v24
	v_exp_f32_e32 v54, v29
	v_sub_f32_e32 v29, v47, v24
	v_exp_f32_e32 v27, v27
	v_sub_f32_e32 v25, v25, v23
	v_exp_f32_e32 v28, v28
	v_exp_f32_e32 v56, v29
	v_exp_f32_e32 v29, v25
	v_sub_f32_e32 v25, v55, v23
	v_exp_f32_e32 v30, v30
	v_sub_f32_e32 v32, v59, v24
	v_exp_f32_e32 v31, v25
	v_sub_f32_e32 v25, v57, v23
	v_exp_f32_e32 v32, v32
	v_sub_f32_e32 v34, v63, v24
	v_exp_f32_e32 v33, v25
	v_sub_f32_e32 v25, v60, v23
	v_exp_f32_e32 v34, v34
	v_exp_f32_e32 v35, v25
	v_sub_f32_e32 v25, v61, v23
	v_pk_add_f32 v[26:27], v[26:27], 0 op_sel_hi:[1,0]
	v_exp_f32_e32 v37, v25
	v_sub_f32_e32 v25, v62, v23
	v_pk_add_f32 v[26:27], v[28:29], v[26:27]
	v_exp_f32_e32 v39, v25
	v_sub_f32_e32 v25, v64, v23
	v_pk_add_f32 v[26:27], v[30:31], v[26:27]
	v_exp_f32_e32 v41, v25
	v_sub_f32_e32 v25, v66, v23
	v_pk_add_f32 v[26:27], v[32:33], v[26:27]
	v_exp_f32_e32 v43, v25
	v_sub_f32_e32 v25, v73, v23
	v_pk_add_f32 v[26:27], v[34:35], v[26:27]
	v_exp_f32_e32 v45, v25
	v_sub_f32_e32 v25, v68, v23
	v_pk_add_f32 v[26:27], v[36:37], v[26:27]
	v_exp_f32_e32 v47, v25
	v_pk_add_f32 v[26:27], v[38:39], v[26:27]
	v_sub_f32_e32 v25, v74, v23
	v_pk_add_f32 v[26:27], v[40:41], v[26:27]
	v_exp_f32_e32 v49, v25
	v_sub_f32_e32 v25, v75, v23
	v_pk_add_f32 v[26:27], v[42:43], v[26:27]
	v_exp_f32_e32 v51, v25
	v_sub_f32_e32 v25, v76, v23
	v_pk_add_f32 v[26:27], v[44:45], v[26:27]
	v_exp_f32_e32 v53, v25
	v_sub_f32_e32 v25, v71, v23
	v_pk_add_f32 v[26:27], v[46:47], v[26:27]
	v_exp_f32_e32 v55, v25
	v_sub_f32_e32 v25, v77, v23
	v_exp_f32_e32 v57, v25
	v_sub_f32_e32 v22, v22, v23
	v_pk_add_f32 v[26:27], v[48:49], v[26:27]
	v_exp_f32_e32 v59, v22
	v_pk_add_f32 v[26:27], v[50:51], v[26:27]
	s_nop 0
	v_pk_add_f32 v[26:27], v[52:53], v[26:27]
	s_nop 0
	v_pk_add_f32 v[26:27], v[54:55], v[26:27]
	s_nop 0
	v_pk_add_f32 v[26:27], v[56:57], v[26:27]
	s_nop 0
	v_pk_fma_f32 v[20:21], v[20:21], v[58:59], v[26:27]
	s_cbranch_scc0 .LBB0_423
	s_mov_b32 s92, s40
	v_mov_b32_e32 v22, v23
	v_mov_b32_e32 v23, v24
	s_mov_b32 s93, s91
	s_branch .LBB0_408

; DEVI void attn_item(const Params& p, int bg, int t0, unsigned char* smem) {
;     ...
;     auto tile_ptrs = [&](int n, const bf16_t*& kp, const bf16_t*& vp) {
;         if (n < n2) { const int c = n < n1 ? n : n - n1; kp = kc + (size_t)c * 4096; vp = vct + (size_t)c * 4096; }
;         else if (n < n3) { const int j = n - n2; kp = ksl + (size_t)j * 4096; vp = vsl + (size_t)j * 4096; }
;         else { const int j = jlo + (n - n3); kp = kwn + (size_t)j * 4096; vp = vwn + (size_t)j * 4096; }
;     ...
;     auto body = [&](auto kc, const int n) {
;         constexpr int KIND = decltype(kc)::value;
;         asm volatile("s_waitcnt vmcnt(0)\n\ts_barrier" ::: "memory");
;         if (n + 1 < ntot) {
;             const bf16_t *kp, *vp; tile_ptrs(n + 1, kp, vp);
;             glds_tile4(gv0, gv1, kp, vp, __builtin_amdgcn_readfirstlane(alds0 + ((n + 1) & 1) * 16384));
.LBB0_444:
	s_add_i32 s91, s13, 1
	s_cmp_ge_i32 s91, s22
	s_cbranch_scc1 .Lawb_b
	s_cmp_ge_u32 s91, s80
	s_mov_b64 s[70:71], -1
	s_cbranch_scc0 .LBB0_451
	s_cmp_ge_i32 s91, s81
	s_mov_b64 s[14:15], -1
	s_cbranch_scc0 .LBB0_448
	s_add_i32 s0, s90, s13
	s_mov_b64 s[14:15], 0

; DEVI float fast_exp2(float x) { return __builtin_amdgcn_exp2f(x); }
; DEVI void attn_item(const Params& p, int bg, int t0, unsigned char* smem) {
;     ...
;         asm volatile("s_waitcnt vmcnt(0)\n\ts_barrier" ::: "memory");
;         if (n + 1 < ntot) {
;             const bf16_t *kp, *vp; tile_ptrs(n + 1, kp, vp);
;             glds_tile4(gv0, gv1, kp, vp, __builtin_amdgcn_readfirstlane(alds0 + ((n + 1) & 1) * 16384));
;     ...
;                 if (is_p2) {
; #pragma unroll
;                     for (int ct = 0; ct < 2; ++ct) {
;                         const int q8 = ct * 4 + (l16 >> 2);
; #pragma unroll
;                         for (int mt = 0; mt < 4; ++mt) {
; #pragma unroll
;                             for (int rr = 0; rr < 4; ++rr) {
;                                 const int c = c0 + mt * 16 + quad * 4 + rr;
;                                 s[ct][mt][rr] = (16 * c + 31 <= tq[ct]) ? fast_exp2(s[ct][mt][rr] * LOG2E - m[ct]) * invl[ct] : 0.f;
;                             }
;                             float gs = (s[ct][mt][0] + s[ct][mt][1]) + (s[ct][mt][2] + s[ct][mt][3]);
;                             float es = s[ct][mt][3];
;                             gs += __int_as_float(__builtin_amdgcn_update_dpp(0, __float_as_int(gs), 0xB1, 0xf, 0xf, false));
;                             gs += __int_as_float(__builtin_amdgcn_update_dpp(0, __float_as_int(gs), 0x4E, 0xf, 0xf, false));
;                             es += __int_as_float(__builtin_amdgcn_update_dpp(0, __float_as_int(es), 0xB1, 0xf, 0xf, false));
;                             es += __int_as_float(__builtin_amdgcn_update_dpp(0, __float_as_int(es), 0x4E, 0xf, 0xf, false));
;                             if (r == 0) {
;                                 const int j = (c0 >> 2) + mt * 4 + quad;
;                                 imp[q8 * 128 + j] = gs;
;                                 impe[q8 * 128 + j] = es;
;                             }
;                         }
.LBB0_453:
	s_ashr_i32 s1, s0, 31
	s_lshl_b64 s[0:1], s[0:1], 13
	s_add_u32 s68, s68, s0
	s_addc_u32 s69, s69, s1
	s_add_u32 s0, s14, s0
	s_addc_u32 s1, s15, s1
	s_add_i32 s13, s89, 0x4000
	s_and_b32 s13, s13, 0x4000
	s_add_i32 s13, s13, s82
	s_waitcnt vmcnt(0)
	s_barrier
	s_mov_b32 s14, m0
	s_mov_b32 m0, s13
	s_nop 0
	global_load_lds_dwordx4 v158, s[68:69]
	s_add_u32 m0, m0, 0x1000
	s_nop 0
	global_load_lds_dwordx4 v159, s[68:69]
	s_add_u32 m0, m0, 0x1000
	s_nop 0
	global_load_lds_dwordx4 v158, s[0:1]
	s_add_u32 m0, m0, 0x1000
	s_nop 0
	global_load_lds_dwordx4 v159, s[0:1]
	s_mov_b32 m0, s14
	s_branch .LBB0_454
.Lawb_b:
	s_waitcnt vmcnt(0)
	s_barrier
.LBB0_454:
	s_and_b32 s0, s89, 0x4000
	v_or_b32_e32 v96, s0, v160
	v_add_u32_e32 v40, v96, v161
	ds_read_b128 v[20:23], v40
	v_add_u32_e32 v44, v96, v162
	ds_read_b128 v[24:27], v44
	ds_read_b128 v[28:31], v40 offset:2048
	ds_read_b128 v[36:39], v44 offset:2048
	ds_read_b128 v[32:35], v40 offset:4096
	ds_read_b128 v[98:101], v44 offset:4096
	ds_read_b128 v[40:43], v40 offset:6144
	ds_read_b128 v[102:105], v44 offset:6144
	s_waitcnt vmcnt(5) lgkmcnt(3)
	v_mfma_f32_16x16x32_bf16 v[110:113], v[32:35], v[4:7], 0
	v_or_b32_e32 v95, 47, v0
	v_cmp_le_i32_e32 vcc, v95, v51
	v_mov_b32_e32 v97, v0
	s_waitcnt vmcnt(2)
	v_mfma_f32_16x16x32_bf16 v[114:117], v[32:35], v[12:15], 0
	v_mfma_f32_16x16x32_bf16 v[44:47], v[20:23], v[4:7], 0
	v_mfma_f32_16x16x32_bf16 v[172:175], v[24:27], v[8:11], v[44:47]
	v_mfma_f32_16x16x32_bf16 v[20:23], v[20:23], v[12:15], 0
	s_waitcnt lgkmcnt(1)
	v_mfma_f32_16x16x32_bf16 v[118:121], v[40:43], v[4:7], 0
	s_nop 4
	v_fma_f32 v50, v172, s77, -v166
	v_mfma_f32_16x16x32_bf16 v[168:171], v[40:43], v[12:15], 0
	s_waitcnt vmcnt(1)
	v_mfma_f32_16x16x32_bf16 v[32:35], v[24:27], v[16:19], v[20:23]
	v_mfma_f32_16x16x32_bf16 v[40:43], v[98:101], v[8:11], v[110:113]
	v_mfma_f32_16x16x32_bf16 v[24:27], v[98:101], v[16:19], v[114:117]
	v_exp_f32_e32 v98, v50
	v_fma_f32 v50, v173, s77, -v166
	v_exp_f32_e32 v99, v50
	v_or_b32_e32 v50, 31, v0
	v_mfma_f32_16x16x32_bf16 v[106:109], v[28:31], v[4:7], 0
	v_mul_f32_e64 v100, v2, v98
	v_mul_f32_e64 v101, v3, v99
	v_cndmask_b32_e32 v98, 0, v101, vcc
	v_cmp_le_i32_e32 vcc, v50, v126
	v_fma_f32 v101, v175, s77, -v166
	v_exp_f32_e32 v101, v101
	v_cndmask_b32_e32 v99, 0, v100, vcc
	v_fma_f32 v100, v174, s77, -v166
	v_exp_f32_e32 v100, v100
	v_mfma_f32_16x16x32_bf16 v[28:31], v[28:31], v[12:15], 0
	v_mul_f32_e32 v101, v2, v101
	v_mul_f32_e32 v100, v2, v100
	v_mfma_f32_16x16x32_bf16 v[44:47], v[36:39], v[8:11], v[106:109]
	s_nop 2
	v_add_u32_e32 v107, 63, v0
	v_cmp_le_i32_e32 vcc, v107, v126
	v_add_u32_e32 v108, 0x4f, v0
	v_mfma_f32_16x16x32_bf16 v[28:31], v[36:39], v[16:19], v[28:31]
	v_cndmask_b32_e32 v100, 0, v100, vcc
	v_cmp_le_i32_e32 vcc, v108, v126
	s_waitcnt lgkmcnt(0)
	v_mfma_f32_16x16x32_bf16 v[36:39], v[102:105], v[8:11], v[118:121]
	v_cndmask_b32_e32 v101, 0, v101, vcc
	v_mfma_f32_16x16x32_bf16 v[20:23], v[102:105], v[16:19], v[168:171]
	v_add_f32_e32 v102, v99, v98
	v_add_f32_e32 v103, v100, v101
	v_add_f32_e32 v102, v102, v103
	v_mov_b32_e32 v103, 0
	v_add_f32_dpp v104, v101, v101 quad_perm:[1,0,3,2] row_mask:0xf bank_mask:0xf bound_ctrl:1
	v_add_f32_dpp v102, v102, v102 quad_perm:[1,0,3,2] row_mask:0xf bank_mask:0xf bound_ctrl:1
	v_mov_b32_e32 v105, 0
	s_nop 0
	v_mov_b32_dpp v103, v102 quad_perm:[2,3,0,1] row_mask:0xf bank_mask:0xf
	v_mov_b32_dpp v105, v104 quad_perm:[2,3,0,1] row_mask:0xf bank_mask:0xf
	s_and_saveexec_b64 s[0:1], s[40:41]
	v_add_f32_e32 v102, v102, v103
	v_add_f32_e32 v103, v104, v105
	ds_write2st64_b32 v94, v102, v103 offset1:16
	s_or_b64 exec, exec, s[0:1]
	v_fma_f32 v44, v44, s77, -v166
	v_exp_f32_e32 v102, v44
	v_fma_f32 v44, v45, s77, -v166
	v_exp_f32_e32 v103, v44
	v_fma_f32 v46, v46, s77, -v166
	v_exp_f32_e32 v46, v46
	v_fma_f32 v47, v47, s77, -v166
	v_or_b32_e32 v45, 0x12f, v97
	v_exp_f32_e32 v47, v47
	v_or_b32_e32 v44, 0x11f, v0
	v_pk_mul_f32 v[104:105], v[2:3], v[102:103]
	v_cmp_le_i32_e32 vcc, v45, v51
	v_add_u32_e32 v109, 0x13f, v0
	v_mul_f32_e32 v46, v2, v46
	v_cndmask_b32_e32 v102, 0, v105, vcc
	v_cmp_le_i32_e32 vcc, v44, v126
	v_add_u32_e32 v111, 0x14f, v0
	v_mov_b32_e32 v112, 0
	v_cndmask_b32_e32 v103, 0, v104, vcc
	v_cmp_le_i32_e32 vcc, v109, v126
	v_add_u32_e32 v110, 16, v94
	s_nop 0
	v_cndmask_b32_e32 v104, 0, v46, vcc
	v_mul_f32_e32 v46, v2, v47
	v_cmp_le_i32_e32 vcc, v111, v126
	s_nop 1
	v_cndmask_b32_e32 v105, 0, v46, vcc
	v_add_f32_e32 v46, v103, v102
	v_add_f32_e32 v47, v104, v105
	v_add_f32_e32 v46, v46, v47
	v_mov_b32_e32 v47, 0
	v_add_f32_dpp v106, v105, v105 quad_perm:[1,0,3,2] row_mask:0xf bank_mask:0xf bound_ctrl:1
	v_add_f32_dpp v46, v46, v46 quad_perm:[1,0,3,2] row_mask:0xf bank_mask:0xf bound_ctrl:1
	s_nop 0
	v_mov_b32_dpp v112, v106 quad_perm:[2,3,0,1] row_mask:0xf bank_mask:0xf
	v_mov_b32_dpp v47, v46 quad_perm:[2,3,0,1] row_mask:0xf bank_mask:0xf
	s_and_saveexec_b64 s[0:1], s[40:41]
	v_add_f32_e32 v46, v46, v47
	v_add_f32_e32 v47, v106, v112
	ds_write2st64_b32 v110, v46, v47 offset1:16
	s_or_b64 exec, exec, s[0:1]
	v_fma_f32 v40, v40, s77, -v166
	v_exp_f32_e32 v46, v40
	v_fma_f32 v40, v41, s77, -v166
	v_exp_f32_e32 v47, v40
	v_fma_f32 v42, v42, s77, -v166
	v_or_b32_e32 v41, 0x22f, v97
	v_fma_f32 v43, v43, s77, -v166
	v_pk_mul_f32 v[112:113], v[2:3], v[46:47]
	v_exp_f32_e32 v47, v42
	v_or_b32_e32 v40, 0x21f, v0
	v_cmp_le_i32_e32 vcc, v41, v51
	v_exp_f32_e32 v106, v43
	v_mul_f32_e32 v47, v2, v47
	v_cndmask_b32_e32 v46, 0, v113, vcc
	v_cmp_le_i32_e32 vcc, v40, v126
	v_add_u32_e32 v114, 0x24f, v0
	v_mov_b32_e32 v115, 0
	v_cndmask_b32_e32 v42, 0, v112, vcc
	v_add_u32_e32 v112, 0x23f, v0
; DEVI float fast_exp2(float x) { return __builtin_amdgcn_exp2f(x); }
; DEVI void attn_item(const Params& p, int bg, int t0, unsigned char* smem) {
;     ...
;                     for (int ct = 0; ct < 2; ++ct) {
;                         const int q8 = ct * 4 + (l16 >> 2);
; #pragma unroll
;                         for (int mt = 0; mt < 4; ++mt) {
; #pragma unroll
;                             for (int rr = 0; rr < 4; ++rr) {
;                                 const int c = c0 + mt * 16 + quad * 4 + rr;
;                                 s[ct][mt][rr] = (16 * c + 31 <= tq[ct]) ? fast_exp2(s[ct][mt][rr] * LOG2E - m[ct]) * invl[ct] : 0.f;
;                             }
;                             float gs = (s[ct][mt][0] + s[ct][mt][1]) + (s[ct][mt][2] + s[ct][mt][3]);
;                             float es = s[ct][mt][3];
;                             gs += __int_as_float(__builtin_amdgcn_update_dpp(0, __float_as_int(gs), 0xB1, 0xf, 0xf, false));
;                             gs += __int_as_float(__builtin_amdgcn_update_dpp(0, __float_as_int(gs), 0x4E, 0xf, 0xf, false));
;                             es += __int_as_float(__builtin_amdgcn_update_dpp(0, __float_as_int(es), 0xB1, 0xf, 0xf, false));
;                             es += __int_as_float(__builtin_amdgcn_update_dpp(0, __float_as_int(es), 0x4E, 0xf, 0xf, false));
;                             if (r == 0) {
;                                 const int j = (c0 >> 2) + mt * 4 + quad;
;                                 imp[q8 * 128 + j] = gs;
;                                 impe[q8 * 128 + j] = es;
;                             }
;                         }
	v_cmp_le_i32_e32 vcc, v112, v126
	v_mov_b32_e32 v117, 0
	s_nop 0
	v_cndmask_b32_e32 v43, 0, v47, vcc
	v_mul_f32_e32 v47, v2, v106
	v_cmp_le_i32_e32 vcc, v114, v126
	v_add_f32_e32 v106, v42, v46
	s_nop 0
	v_cndmask_b32_e32 v47, 0, v47, vcc
	v_add_f32_e32 v113, v43, v47
	v_add_f32_e32 v106, v106, v113
	v_add_f32_dpp v116, v47, v47 quad_perm:[1,0,3,2] row_mask:0xf bank_mask:0xf bound_ctrl:1
	v_add_u32_e32 v113, 32, v94
	v_add_f32_dpp v106, v106, v106 quad_perm:[1,0,3,2] row_mask:0xf bank_mask:0xf bound_ctrl:1
	v_mov_b32_dpp v117, v116 quad_perm:[2,3,0,1] row_mask:0xf bank_mask:0xf
	s_nop 0
	v_mov_b32_dpp v115, v106 quad_perm:[2,3,0,1] row_mask:0xf bank_mask:0xf
	s_and_saveexec_b64 s[0:1], s[40:41]
	v_add_f32_e32 v106, v106, v115
	v_add_f32_e32 v115, v116, v117
	ds_write2st64_b32 v113, v106, v115 offset1:16
	s_or_b64 exec, exec, s[0:1]
	v_fma_f32 v36, v36, s77, -v166
	v_exp_f32_e32 v116, v36
	v_fma_f32 v36, v37, s77, -v166
	v_exp_f32_e32 v117, v36
	v_or_b32_e32 v37, 0x32f, v97
	v_or_b32_e32 v36, 0x31f, v0
	v_cmp_le_i32_e32 vcc, v37, v51
	v_pk_mul_f32 v[116:117], v[2:3], v[116:117]
	v_fma_f32 v38, v38, s77, -v166
	v_cndmask_b32_e32 v97, 0, v117, vcc
	v_exp_f32_e32 v106, v38
	v_cmp_le_i32_e32 vcc, v36, v126
	v_fma_f32 v39, v39, s77, -v166
	v_add_u32_e32 v115, 0x33f, v0
	v_cndmask_b32_e32 v38, 0, v116, vcc
	v_exp_f32_e32 v116, v39
	v_mul_f32_e32 v106, v2, v106
	v_cmp_le_i32_e32 vcc, v115, v126
	v_add_u32_e32 v117, 0x34f, v0
	v_mov_b32_e32 v119, 0
	v_cndmask_b32_e32 v39, 0, v106, vcc
	v_mul_f32_e32 v106, v2, v116
	v_cmp_le_i32_e32 vcc, v117, v126
	v_add_f32_e32 v116, v38, v97
	v_mov_b32_e32 v121, 0
	v_cndmask_b32_e32 v106, 0, v106, vcc
	v_add_f32_e32 v118, v39, v106
	v_add_f32_e32 v116, v116, v118
	v_add_f32_dpp v120, v106, v106 quad_perm:[1,0,3,2] row_mask:0xf bank_mask:0xf bound_ctrl:1
	s_nop 0
	v_add_f32_dpp v118, v116, v116 quad_perm:[1,0,3,2] row_mask:0xf bank_mask:0xf bound_ctrl:1
	v_mov_b32_dpp v121, v120 quad_perm:[2,3,0,1] row_mask:0xf bank_mask:0xf
	v_add_u32_e32 v116, 48, v94
	v_mov_b32_dpp v119, v118 quad_perm:[2,3,0,1] row_mask:0xf bank_mask:0xf
	s_and_saveexec_b64 s[0:1], s[40:41]
	v_add_f32_e32 v118, v118, v119
	v_add_f32_e32 v119, v120, v121
	ds_write2st64_b32 v116, v118, v119 offset1:16
	s_or_b64 exec, exec, s[0:1]
	v_fma_f32 v32, v32, s77, -v165
	v_fma_f32 v33, v33, s77, -v165
	v_exp_f32_e32 v32, v32
	v_exp_f32_e32 v33, v33
	v_fma_f32 v35, v35, s77, -v165
	v_exp_f32_e32 v35, v35
	v_cmp_le_i32_e32 vcc, v95, v93
	v_pk_mul_f32 v[118:119], v[48:49], v[32:33]
	v_fma_f32 v33, v34, s77, -v165
	v_exp_f32_e32 v34, v33
	v_cndmask_b32_e32 v32, 0, v119, vcc
	v_cmp_le_i32_e32 vcc, v50, v124
	v_mul_f32_e32 v35, v48, v35
	v_mul_f32_e32 v34, v48, v34
	v_cndmask_b32_e32 v33, 0, v118, vcc
	v_cmp_le_i32_e32 vcc, v107, v124
	v_add_f32_e32 v50, v33, v32
	s_nop 0
	v_cndmask_b32_e32 v34, 0, v34, vcc
	v_cmp_le_i32_e32 vcc, v108, v124
	v_mov_b32_e32 v108, 0
	s_nop 0
	v_cndmask_b32_e32 v35, 0, v35, vcc
	v_add_f32_e32 v95, v34, v35
	v_add_f32_e32 v50, v50, v95
	v_mov_b32_e32 v95, 0
	v_add_f32_dpp v107, v35, v35 quad_perm:[1,0,3,2] row_mask:0xf bank_mask:0xf bound_ctrl:1
	v_add_f32_dpp v50, v50, v50 quad_perm:[1,0,3,2] row_mask:0xf bank_mask:0xf bound_ctrl:1
	s_nop 0
	v_mov_b32_dpp v108, v107 quad_perm:[2,3,0,1] row_mask:0xf bank_mask:0xf
	v_mov_b32_dpp v95, v50 quad_perm:[2,3,0,1] row_mask:0xf bank_mask:0xf
	s_and_saveexec_b64 s[0:1], s[40:41]
	v_add_f32_e32 v50, v50, v95
	v_add_f32_e32 v95, v107, v108
	ds_write2st64_b32 v94, v50, v95 offset0:8 offset1:24
	s_or_b64 exec, exec, s[0:1]
	v_fma_f32 v28, v28, s77, -v165
	v_fma_f32 v29, v29, s77, -v165
	v_exp_f32_e32 v28, v28
	v_exp_f32_e32 v29, v29
; DEVI float fast_exp2(float x) { return __builtin_amdgcn_exp2f(x); }
; DEVI void attn_item(const Params& p, int bg, int t0, unsigned char* smem) {
;     ...
;                     for (int ct = 0; ct < 2; ++ct) {
;                         const int q8 = ct * 4 + (l16 >> 2);
; #pragma unroll
;                         for (int mt = 0; mt < 4; ++mt) {
; #pragma unroll
;                             for (int rr = 0; rr < 4; ++rr) {
;                                 const int c = c0 + mt * 16 + quad * 4 + rr;
;                                 s[ct][mt][rr] = (16 * c + 31 <= tq[ct]) ? fast_exp2(s[ct][mt][rr] * LOG2E - m[ct]) * invl[ct] : 0.f;
;                             }
;                             float gs = (s[ct][mt][0] + s[ct][mt][1]) + (s[ct][mt][2] + s[ct][mt][3]);
;                             float es = s[ct][mt][3];
;                             gs += __int_as_float(__builtin_amdgcn_update_dpp(0, __float_as_int(gs), 0xB1, 0xf, 0xf, false));
;                             gs += __int_as_float(__builtin_amdgcn_update_dpp(0, __float_as_int(gs), 0x4E, 0xf, 0xf, false));
;                             es += __int_as_float(__builtin_amdgcn_update_dpp(0, __float_as_int(es), 0xB1, 0xf, 0xf, false));
;                             es += __int_as_float(__builtin_amdgcn_update_dpp(0, __float_as_int(es), 0x4E, 0xf, 0xf, false));
;                             if (r == 0) {
;                                 const int j = (c0 >> 2) + mt * 4 + quad;
;                                 imp[q8 * 128 + j] = gs;
;                                 impe[q8 * 128 + j] = es;
;                             }
;                         }
	v_fma_f32 v31, v31, s77, -v165
	v_exp_f32_e32 v31, v31
	v_cmp_le_i32_e32 vcc, v45, v93
	v_pk_mul_f32 v[118:119], v[48:49], v[28:29]
	v_fma_f32 v29, v30, s77, -v165
	v_exp_f32_e32 v30, v29
	v_cndmask_b32_e32 v28, 0, v119, vcc
	v_cmp_le_i32_e32 vcc, v44, v124
	v_mul_f32_e32 v31, v48, v31
	v_mul_f32_e32 v30, v48, v30
	v_cndmask_b32_e32 v29, 0, v118, vcc
	v_cmp_le_i32_e32 vcc, v109, v124
	v_add_f32_e32 v44, v29, v28
	v_mov_b32_e32 v95, 0
	v_cndmask_b32_e32 v30, 0, v30, vcc
	v_cmp_le_i32_e32 vcc, v111, v124
	s_nop 1
	v_cndmask_b32_e32 v31, 0, v31, vcc
	v_add_f32_e32 v45, v30, v31
	v_add_f32_e32 v44, v44, v45
	v_mov_b32_e32 v45, 0
	v_add_f32_dpp v50, v31, v31 quad_perm:[1,0,3,2] row_mask:0xf bank_mask:0xf bound_ctrl:1
	v_add_f32_dpp v44, v44, v44 quad_perm:[1,0,3,2] row_mask:0xf bank_mask:0xf bound_ctrl:1
	s_nop 0
	v_mov_b32_dpp v95, v50 quad_perm:[2,3,0,1] row_mask:0xf bank_mask:0xf
	v_mov_b32_dpp v45, v44 quad_perm:[2,3,0,1] row_mask:0xf bank_mask:0xf
	s_and_saveexec_b64 s[0:1], s[40:41]
	v_add_f32_e32 v44, v44, v45
	v_add_f32_e32 v45, v50, v95
	ds_write2st64_b32 v110, v44, v45 offset0:8 offset1:24
	s_or_b64 exec, exec, s[0:1]
	v_fma_f32 v24, v24, s77, -v165
	v_fma_f32 v25, v25, s77, -v165
	v_exp_f32_e32 v24, v24
	v_exp_f32_e32 v25, v25
	v_fma_f32 v27, v27, s77, -v165
	v_exp_f32_e32 v27, v27
	v_cmp_le_i32_e32 vcc, v41, v93
	v_pk_mul_f32 v[44:45], v[48:49], v[24:25]
	v_fma_f32 v25, v26, s77, -v165
	v_exp_f32_e32 v26, v25
	v_cndmask_b32_e32 v24, 0, v45, vcc
	v_cmp_le_i32_e32 vcc, v40, v124
	v_mul_f32_e32 v27, v48, v27
	v_mul_f32_e32 v26, v48, v26
	v_cndmask_b32_e32 v25, 0, v44, vcc
	v_cmp_le_i32_e32 vcc, v112, v124
	v_add_f32_e32 v40, v25, v24
	v_mov_b32_e32 v45, 0
	v_cndmask_b32_e32 v26, 0, v26, vcc
	v_cmp_le_i32_e32 vcc, v114, v124
	s_nop 1
	v_cndmask_b32_e32 v27, 0, v27, vcc
	v_add_f32_e32 v41, v26, v27
	v_add_f32_e32 v40, v40, v41
	v_mov_b32_e32 v41, 0
	v_add_f32_dpp v44, v27, v27 quad_perm:[1,0,3,2] row_mask:0xf bank_mask:0xf bound_ctrl:1
	v_add_f32_dpp v40, v40, v40 quad_perm:[1,0,3,2] row_mask:0xf bank_mask:0xf bound_ctrl:1
	s_nop 0
	v_mov_b32_dpp v45, v44 quad_perm:[2,3,0,1] row_mask:0xf bank_mask:0xf
	v_mov_b32_dpp v41, v40 quad_perm:[2,3,0,1] row_mask:0xf bank_mask:0xf
	s_and_saveexec_b64 s[0:1], s[40:41]
	v_add_f32_e32 v40, v40, v41
	v_add_f32_e32 v41, v44, v45
	ds_write2st64_b32 v113, v40, v41 offset0:8 offset1:24
	s_or_b64 exec, exec, s[0:1]
	v_fma_f32 v20, v20, s77, -v165
	v_fma_f32 v21, v21, s77, -v165
	v_exp_f32_e32 v20, v20
	v_exp_f32_e32 v21, v21
	v_fma_f32 v23, v23, s77, -v165
	v_exp_f32_e32 v23, v23
	v_cmp_le_i32_e32 vcc, v37, v93
	v_pk_mul_f32 v[40:41], v[48:49], v[20:21]
	v_fma_f32 v21, v22, s77, -v165
	v_exp_f32_e32 v22, v21
	v_cndmask_b32_e32 v20, 0, v41, vcc
	v_cmp_le_i32_e32 vcc, v36, v124
	v_mul_f32_e32 v23, v48, v23
	v_mul_f32_e32 v22, v48, v22
	v_cndmask_b32_e32 v21, 0, v40, vcc
	v_cmp_le_i32_e32 vcc, v115, v124
	v_add_f32_e32 v36, v21, v20
	v_mov_b32_e32 v41, 0
	v_cndmask_b32_e32 v22, 0, v22, vcc
	v_cmp_le_i32_e32 vcc, v117, v124
	s_nop 1
	v_cndmask_b32_e32 v23, 0, v23, vcc
	v_add_f32_e32 v37, v22, v23
	v_add_f32_e32 v36, v36, v37
	v_mov_b32_e32 v37, 0
	v_add_f32_dpp v40, v23, v23 quad_perm:[1,0,3,2] row_mask:0xf bank_mask:0xf bound_ctrl:1
	v_add_f32_dpp v36, v36, v36 quad_perm:[1,0,3,2] row_mask:0xf bank_mask:0xf bound_ctrl:1
	s_nop 0
	v_mov_b32_dpp v41, v40 quad_perm:[2,3,0,1] row_mask:0xf bank_mask:0xf
	v_mov_b32_dpp v37, v36 quad_perm:[2,3,0,1] row_mask:0xf bank_mask:0xf
	s_and_saveexec_b64 s[0:1], s[40:41]
	s_cbranch_execz .LBB0_443
	v_add_f32_e32 v36, v36, v37
	v_add_f32_e32 v37, v40, v41
	ds_write2st64_b32 v116, v36, v37 offset0:8 offset1:24
	s_branch .LBB0_443

; DEVI void attn_item(const Params& p, int bg, int t0, unsigned char* smem) {
;     ...
;     auto tile_ptrs = [&](int n, const bf16_t*& kp, const bf16_t*& vp) {
;         if (n < n2) { const int c = n < n1 ? n : n - n1; kp = kc + (size_t)c * 4096; vp = vct + (size_t)c * 4096; }
;         else if (n < n3) { const int j = n - n2; kp = ksl + (size_t)j * 4096; vp = vsl + (size_t)j * 4096; }
;         else { const int j = jlo + (n - n3); kp = kwn + (size_t)j * 4096; vp = vwn + (size_t)j * 4096; }
;     ...
;     auto body = [&](auto kc, const int n) {
;         constexpr int KIND = decltype(kc)::value;
;         asm volatile("s_waitcnt vmcnt(0)\n\ts_barrier" ::: "memory");
;         if (n + 1 < ntot) {
;             const bf16_t *kp, *vp; tile_ptrs(n + 1, kp, vp);
;             glds_tile4(gv0, gv1, kp, vp, __builtin_amdgcn_readfirstlane(alds0 + ((n + 1) & 1) * 16384));
.LBB0_492:
	s_add_i32 s89, s13, 1
	s_cmp_ge_i32 s89, s22
	s_cbranch_scc1 .Lawb_c
	s_cmp_ge_u32 s89, s80
	s_mov_b64 s[68:69], -1
	s_cbranch_scc0 .LBB0_499
	s_cmp_ge_i32 s89, s81
	s_mov_b64 s[14:15], -1
	s_cbranch_scc0 .LBB0_496
	s_add_i32 s0, s91, s13
	s_mov_b64 s[14:15], 0

; DEVI void attn_item(const Params& p, int bg, int t0, unsigned char* smem) {
;     ...
;         if (is_slc && !elem) {
;             const unsigned aw = __builtin_amdgcn_readfirstlane(anyw[jt >> 5] | anyw[4 + (jt >> 5)]);
;             any_act = (aw >> (jt & 31)) & 1u;
;         }
;         if (any_act) {
;             f32x4 s[2][4];
;             {
;                 bf16x8 k0[4], k1[4];
; #pragma unroll
;                 for (int mt = 0; mt < 4; ++mt) {
;                     k0[mt] = *(const bf16x8*)(cK + (mt * 16 + l16) * 128 + ((quad ^ rsw) * 16));
;                     k1[mt] = *(const bf16x8*)(cK + (mt * 16 + l16) * 128 + (((4 + quad) ^ rsw) * 16));
;                 }
; #pragma unroll
;                 for (int mt = 0; mt < 4; ++mt)
; #pragma unroll
;                     for (int ct = 0; ct < 2; ++ct) s[ct][mt] = mfma16(k0[mt], qf[ct][0], (f32x4){0.f, 0.f, 0.f, 0.f});
; #pragma unroll
;                 for (int mt = 0; mt < 4; ++mt)
; #pragma unroll
;                     for (int ct = 0; ct < 2; ++ct) s[ct][mt] = mfma16(k1[mt], qf[ct][1], s[ct][mt]);
;     ...
;                         for (int ct = 0; ct < 2; ++ct) mr[ct] = rmax16(mr[ct]);
; #pragma unroll
;                         for (int ct = 0; ct < 2; ++ct) mr[ct] = rmax32(mr[ct]);
;                         float cand[2];
;                         bool need = false;
; #pragma unroll
;                         for (int ct = 0; ct < 2; ++ct) {
;                             cand[ct] = fmaxf(m[ct], __builtin_fmaf(mr[ct], LOG2E, bias[ct]));
;                             need = need || (cand[ct] - m[ct] > 8.0f);
;                         }
;                         const bool resc = __builtin_amdgcn_ballot_w64(need) != 0;
; #pragma unroll
;                         for (int ct = 0; ct < 2; ++ct) {
;                             mn[ct] = resc ? cand[ct] : m[ct];
;                             const float nb = bias[ct] - mn[ct];
; #pragma unroll
;                             for (int mt = 0; mt < 4; ++mt)
; #pragma unroll
;                                 for (int rr = 0; rr < 4; ++rr) { s[ct][mt][rr] = fast_exp2(__builtin_fmaf(s[ct][mt][rr], LOG2E, nb)); }
;                         }
;                     }
;                     float al[2];
; #pragma unroll
;                     for (int ct = 0; ct < 2; ++ct) {
;                         al[ct] = fast_exp2(m[ct] - mn[ct]);
;                         m[ct] = mn[ct];
.LBB0_501:
	s_ashr_i32 s1, s0, 31
	s_lshl_b64 s[0:1], s[0:1], 13
	s_add_u32 s40, s40, s0
	s_addc_u32 s41, s41, s1
	s_add_u32 s0, s14, s0
	s_addc_u32 s1, s15, s1
	s_add_i32 s14, s71, 0x4000
	s_and_b32 s14, s14, 0x4000
	s_add_i32 s14, s14, s82
	s_waitcnt vmcnt(0)
	s_barrier
	s_mov_b32 s15, m0
	s_mov_b32 m0, s14
	s_nop 0
	global_load_lds_dwordx4 v158, s[40:41]
	s_add_u32 m0, m0, 0x1000
	s_nop 0
	global_load_lds_dwordx4 v159, s[40:41]
	s_add_u32 m0, m0, 0x1000
	s_nop 0
	global_load_lds_dwordx4 v158, s[0:1]
	s_add_u32 m0, m0, 0x1000
	s_nop 0
	global_load_lds_dwordx4 v159, s[0:1]
	s_mov_b32 m0, s15
	s_branch .LBB0_502
.Lawb_c:
	s_waitcnt vmcnt(0)
	s_barrier
.LBB0_502:
	s_add_i32 s0, s70, s13
	s_ashr_i32 s1, s0, 5
	s_lshl_b32 s13, s1, 2
	s_add_i32 s13, s10, s13
	v_mov_b32_e32 v0, s13
	v_add_u32_e32 v0, 0xa000, v0
	ds_read2_b32 v[92:93], v0 offset0:32 offset1:36
	s_lshl_b32 s0, 1, s0
	s_waitcnt lgkmcnt(0)
	v_or_b32_e32 v0, v93, v92
	s_nop 0
	v_readfirstlane_b32 s13, v0
	s_and_b32 s13, s13, s0
	s_cmp_eq_u32 s13, 0
	s_cbranch_scc1 .LBB0_490
	s_and_b32 s13, s71, 0x4000
	v_or_b32_e32 v171, s13, v160
	v_add_u32_e32 v0, v171, v161
	ds_read_b128 v[92:95], v0
	v_add_u32_e32 v2, v171, v162
	ds_read_b128 v[96:99], v2
	ds_read_b128 v[100:103], v0 offset:2048
	ds_read_b128 v[108:111], v2 offset:2048
	ds_read_b128 v[104:107], v0 offset:4096
	ds_read_b128 v[172:175], v2 offset:4096
	ds_read_b128 v[112:115], v0 offset:6144
	ds_read_b128 v[176:179], v2 offset:6144
	s_waitcnt vmcnt(5) lgkmcnt(3)
	v_mfma_f32_16x16x32_bf16 v[184:187], v[104:107], v[4:7], 0
	v_lshl_add_u32 v0, s1, 2, v170
	v_add_u32_e32 v0, 0xa000, v0
	s_waitcnt vmcnt(2)
	v_mfma_f32_16x16x32_bf16 v[188:191], v[104:107], v[12:15], 0
	v_mfma_f32_16x16x32_bf16 v[116:119], v[92:95], v[4:7], 0
	v_mfma_f32_16x16x32_bf16 v[92:95], v[92:95], v[12:15], 0
	s_waitcnt lgkmcnt(1)
	v_mfma_f32_16x16x32_bf16 v[192:195], v[112:115], v[4:7], 0
	v_mfma_f32_16x16x32_bf16 v[196:199], v[112:115], v[12:15], 0
	v_mfma_f32_16x16x32_bf16 v[120:123], v[96:99], v[8:11], v[116:119]
	s_waitcnt vmcnt(1)
	v_mfma_f32_16x16x32_bf16 v[104:107], v[96:99], v[16:19], v[92:95]
	v_mfma_f32_16x16x32_bf16 v[112:115], v[172:175], v[8:11], v[184:187]
	s_nop 4
	v_mfma_f32_16x16x32_bf16 v[96:99], v[172:175], v[16:19], v[188:191]
	ds_read2_b32 v[174:175], v0 offset1:16
	s_waitcnt lgkmcnt(0)
	v_and_b32_e32 v0, s0, v174
	v_mfma_f32_16x16x32_bf16 v[180:183], v[100:103], v[4:7], 0
	v_cmp_eq_u32_e32 vcc, 0, v0
	v_and_b32_e32 v0, s0, v175
	v_mfma_f32_16x16x32_bf16 v[100:103], v[100:103], v[12:15], 0
	v_cndmask_b32_e32 v173, 0, v147, vcc
	v_cmp_eq_u32_e32 vcc, 0, v0
	v_mfma_f32_16x16x32_bf16 v[116:119], v[108:111], v[8:11], v[180:183]
	v_max_f32_e32 v0, v120, v121
	v_max_f32_e32 v2, v122, v123
	v_mfma_f32_16x16x32_bf16 v[100:103], v[108:111], v[16:19], v[100:103]
	v_cndmask_b32_e32 v172, 0, v147, vcc
	s_nop 2
	v_mfma_f32_16x16x32_bf16 v[108:111], v[176:179], v[8:11], v[192:195]
	v_max_f32_e32 v167, v118, v119
	v_max3_f32 v167, v116, v117, v167
	v_max3_f32 v0, v0, v2, v167
	v_max_f32_e32 v2, v114, v115
	s_nop 1
	v_max_f32_e32 v167, v110, v111
	v_max3_f32 v2, v112, v113, v2
	v_max3_f32 v167, v108, v109, v167
	v_max3_f32 v0, v0, v2, v167
	v_max_f32_e32 v2, v104, v105
	v_mfma_f32_16x16x32_bf16 v[92:95], v[176:179], v[16:19], v[196:199]
	v_max_f32_e32 v167, v106, v107
	v_max_f32_e32 v168, v102, v103
	v_max3_f32 v168, v100, v101, v168
	v_max3_f32 v2, v2, v167, v168
	v_max_f32_e32 v167, v98, v99
	v_max_f32_e32 v174, v94, v94
	v_max_f32_e32 v168, v174, v95
	v_max3_f32 v167, v96, v97, v167
	v_max3_f32 v168, v92, v93, v168
	v_max3_f32 v2, v2, v167, v168
	v_mov_b32_e32 v167, v0
	s_nop 1
	v_permlane16_swap_b32_e32 v0, v167
	v_max_f32_e32 v167, v167, v167
	v_max_f32_e32 v0, v0, v0
	v_max_f32_e32 v0, v0, v167
	v_mov_b32_e32 v167, v2
	s_nop 1
	v_permlane16_swap_b32_e32 v2, v167
	v_max_f32_e32 v167, v167, v167
	v_max_f32_e32 v2, v2, v2
	v_max_f32_e32 v2, v2, v167
	v_mov_b32_e32 v167, v0
	s_nop 1
	v_permlane32_swap_b32_e32 v0, v167
	v_max_f32_e32 v167, v167, v167
	v_max_f32_e32 v0, v0, v0
	v_max_f32_e32 v0, v0, v167
	v_mov_b32_e32 v167, v2
	s_nop 1
	v_permlane32_swap_b32_e32 v2, v167
	v_max_f32_e32 v167, v167, v167
	v_max_f32_e32 v2, v2, v2
	v_max_f32_e32 v2, v2, v167
	v_fmamk_f32 v0, v0, 0x3fb8aa3b, v173
	v_fmamk_f32 v2, v2, 0x3fb8aa3b, v172
	v_max_f32_e32 v0, v166, v0
	v_max_f32_e32 v2, v165, v2
	v_sub_f32_e32 v167, v0, v166
	v_sub_f32_e32 v168, v2, v165
	v_max_f32_e32 v167, v167, v168
	v_cmp_lt_f32_e32 vcc, s16, v167
	s_cmp_eq_u64 vcc, 0
	s_cselect_b64 vcc, -1, 0
	v_cndmask_b32_e32 v167, v0, v166, vcc
	v_cndmask_b32_e32 v168, v2, v165, vcc
	v_sub_f32_e32 v0, v166, v167
	v_exp_f32_e32 v2, v0
	v_sub_f32_e32 v0, v165, v168
	v_exp_f32_e32 v0, v0
	v_cmp_neq_f32_e32 vcc, 1.0, v2
	v_cmp_neq_f32_e64 s[0:1], 1.0, v0
	s_or_b64 vcc, vcc, s[0:1]
	s_cbranch_vccz .LBB0_505
	v_pk_mul_f32 v[82:83], v[82:83], v[2:3] op_sel_hi:[1,0]
	v_pk_mul_f32 v[80:81], v[80:81], v[2:3] op_sel_hi:[1,0]
	v_pk_mul_f32 v[74:75], v[74:75], v[2:3] op_sel_hi:[1,0]
	v_pk_mul_f32 v[72:73], v[72:73], v[2:3] op_sel_hi:[1,0]
	v_pk_mul_f32 v[66:67], v[66:67], v[2:3] op_sel_hi:[1,0]
	v_pk_mul_f32 v[64:65], v[64:65], v[2:3] op_sel_hi:[1,0]
	v_pk_mul_f32 v[58:59], v[58:59], v[2:3] op_sel_hi:[1,0]
	v_pk_mul_f32 v[56:57], v[56:57], v[2:3] op_sel_hi:[1,0]
	v_pk_mul_f32 v[78:79], v[78:79], v[0:1] op_sel_hi:[1,0]
	v_pk_mul_f32 v[76:77], v[76:77], v[0:1] op_sel_hi:[1,0]
	v_pk_mul_f32 v[70:71], v[70:71], v[0:1] op_sel_hi:[1,0]
	v_pk_mul_f32 v[68:69], v[68:69], v[0:1] op_sel_hi:[1,0]
	v_pk_mul_f32 v[62:63], v[62:63], v[0:1] op_sel_hi:[1,0]
	v_pk_mul_f32 v[60:61], v[60:61], v[0:1] op_sel_hi:[1,0]
	v_pk_mul_f32 v[54:55], v[54:55], v[0:1] op_sel_hi:[1,0]
	v_pk_mul_f32 v[52:53], v[52:53], v[0:1] op_sel_hi:[1,0]
	v_pk_mul_f32 v[86:87], v[86:87], v[2:3] op_sel_hi:[1,0]
	v_pk_mul_f32 v[84:85], v[84:85], v[2:3] op_sel_hi:[1,0]
	v_pk_mul_f32 v[90:91], v[90:91], v[0:1] op_sel_hi:[1,0]
	v_pk_mul_f32 v[88:89], v[88:89], v[0:1] op_sel_hi:[1,0]

; DEVI void attn_item(const Params& p, int bg, int t0, unsigned char* smem) {
;     ...
;     auto tile_ptrs = [&](int n, const bf16_t*& kp, const bf16_t*& vp) {
;         if (n < n2) { const int c = n < n1 ? n : n - n1; kp = kc + (size_t)c * 4096; vp = vct + (size_t)c * 4096; }
;         else if (n < n3) { const int j = n - n2; kp = ksl + (size_t)j * 4096; vp = vsl + (size_t)j * 4096; }
;         else { const int j = jlo + (n - n3); kp = kwn + (size_t)j * 4096; vp = vwn + (size_t)j * 4096; }
;     ...
;     auto body = [&](auto kc, const int n) {
;         constexpr int KIND = decltype(kc)::value;
;         asm volatile("s_waitcnt vmcnt(0)\n\ts_barrier" ::: "memory");
;         if (n + 1 < ntot) {
;             const bf16_t *kp, *vp; tile_ptrs(n + 1, kp, vp);
;             glds_tile4(gv0, gv1, kp, vp, __builtin_amdgcn_readfirstlane(alds0 + ((n + 1) & 1) * 16384));
.LBB0_538:
	s_mov_b32 s71, s91
	s_add_i32 s91, s91, 1
	s_cmp_ge_i32 s91, s22
	s_cselect_b64 s[38:39], -1, 0
	s_and_b64 vcc, exec, s[38:39]
	s_cbranch_vccnz .Lawb_d
	s_add_i32 s1, s89, 2
	s_cmp_ge_u32 s91, s80
	s_mov_b64 s[68:69], -1
	s_cbranch_scc0 .LBB0_545
	s_cmp_ge_i32 s91, s81
	s_mov_b64 s[14:15], -1
	s_cbranch_scc0 .LBB0_542
	s_add_i32 s0, s11, s71
	s_mov_b64 s[14:15], 0

; DEVI f32x4 mfma16(bf16x8 a, bf16x8 b, f32x4 c) { return __builtin_amdgcn_mfma_f32_16x16x32_bf16(a, b, c, 0, 0, 0); }
; DEVI void attn_item(const Params& p, int bg, int t0, unsigned char* smem) {
;     ...
;             f32x4 s[2][4];
;             {
;                 bf16x8 k0[4], k1[4];
; #pragma unroll
;                 for (int mt = 0; mt < 4; ++mt) {
;                     k0[mt] = *(const bf16x8*)(cK + (mt * 16 + l16) * 128 + ((quad ^ rsw) * 16));
;                     k1[mt] = *(const bf16x8*)(cK + (mt * 16 + l16) * 128 + (((4 + quad) ^ rsw) * 16));
;                 }
; #pragma unroll
;                 for (int mt = 0; mt < 4; ++mt)
; #pragma unroll
;                     for (int ct = 0; ct < 2; ++ct) s[ct][mt] = mfma16(k0[mt], qf[ct][0], (f32x4){0.f, 0.f, 0.f, 0.f});
; #pragma unroll
;                 for (int mt = 0; mt < 4; ++mt)
; #pragma unroll
;                     for (int ct = 0; ct < 2; ++ct) s[ct][mt] = mfma16(k1[mt], qf[ct][1], s[ct][mt]);
;     ...
;                     if (elem) {
; #pragma unroll
;                         for (int ct = 0; ct < 2; ++ct) {
;                             mr[ct] = NINF;
; #pragma unroll
;                             for (int mt = 0; mt < 4; ++mt)
; #pragma unroll
;                                 for (int rr = 0; rr < 4; ++rr) {
;                                     float x = __builtin_fmaf(s[ct][mt][rr], LOG2E, bias[ct]);
;                                     const int dist = tq[ct] - (jt * 64 + mt * 16 + quad * 4 + rr);
;                                     x = (dist >= 0 && dist < wlim) ? x : NINF;
;                                     s[ct][mt][rr] = x; mr[ct] = fmaxf(mr[ct], x);
;                                 }
.LBB0_547:
	s_ashr_i32 s1, s0, 31
	s_lshl_b64 s[0:1], s[0:1], 13
	s_add_u32 s40, s40, s0
	s_addc_u32 s41, s41, s1
	s_add_u32 s0, s14, s0
	s_addc_u32 s1, s15, s1
	s_and_b32 s13, s70, 0x4000
	s_add_i32 s13, s13, s82
	s_waitcnt vmcnt(0)
	s_barrier
	s_mov_b32 s14, m0
	s_mov_b32 m0, s13
	s_nop 0
	global_load_lds_dwordx4 v158, s[40:41]
	s_add_u32 m0, m0, 0x1000
	s_nop 0
	global_load_lds_dwordx4 v159, s[40:41]
	s_add_u32 m0, m0, 0x1000
	s_nop 0
	global_load_lds_dwordx4 v158, s[0:1]
	s_add_u32 m0, m0, 0x1000
	s_nop 0
	global_load_lds_dwordx4 v159, s[0:1]
	s_mov_b32 m0, s14
	s_branch .LBB0_548
.Lawb_d:
	s_waitcnt vmcnt(0)
	s_barrier
.LBB0_548:
	s_addk_i32 s70, 0x4000
	s_and_b32 s0, s70, 0x4000
	v_or_b32_e32 v3, s0, v160
	v_add_u32_e32 v0, v3, v161
	ds_read_b128 v[168:171], v0
	v_add_u32_e32 v2, v3, v162
	ds_read_b128 v[172:175], v2
	ds_read_b128 v[176:179], v0 offset:2048
	ds_read_b128 v[180:183], v2 offset:2048
	ds_read_b128 v[184:187], v0 offset:4096
	ds_read_b128 v[188:191], v2 offset:4096
	ds_read_b128 v[192:195], v0 offset:6144
	ds_read_b128 v[196:199], v2 offset:6144
	s_waitcnt lgkmcnt(5)
	v_mfma_f32_16x16x32_bf16 v[204:207], v[176:179], v[4:7], 0
	v_add_u32_e32 v2, s10, v69
	v_add_u32_e32 v70, 0x1fe0, v2
	v_cmp_gt_u32_e32 vcc, s76, v70
	v_mfma_f32_16x16x32_bf16 v[176:179], v[176:179], v[12:15], 0
	v_add_u32_e32 v70, 0x1fdf, v2
	v_add_u32_e32 v71, 0x1fde, v2
	v_mfma_f32_16x16x32_bf16 v[200:203], v[168:171], v[4:7], 0
	v_mfma_f32_16x16x32_bf16 v[168:171], v[168:171], v[12:15], 0
	v_mfma_f32_16x16x32_bf16 v[200:203], v[172:175], v[8:11], v[200:203]
	s_waitcnt lgkmcnt(3)
	v_mfma_f32_16x16x32_bf16 v[208:211], v[184:187], v[4:7], 0
	v_mfma_f32_16x16x32_bf16 v[216:219], v[172:175], v[16:19], v[168:171]
	s_nop 4
	v_fma_f32 v0, v200, s77, 0
	v_cndmask_b32_e32 v134, v147, v0, vcc
	v_fma_f32 v0, v201, s77, 0
	v_mfma_f32_16x16x32_bf16 v[170:173], v[180:183], v[8:11], v[204:207]
	v_cmp_gt_u32_e32 vcc, s76, v70
	v_fma_f32 v70, v202, s77, 0
	s_nop 0
	v_cndmask_b32_e32 v163, v147, v0, vcc
	v_cmp_gt_u32_e32 vcc, s76, v71
	v_add_u32_e32 v71, 0x1fdd, v2
	s_waitcnt lgkmcnt(1)
	v_mfma_f32_16x16x32_bf16 v[212:215], v[192:195], v[4:7], 0
	v_cndmask_b32_e32 v167, v147, v70, vcc
	v_fma_f32 v70, v203, s77, 0
	v_cmp_gt_u32_e32 vcc, s76, v71
	v_add_u32_e32 v71, 0x1fd0, v2
	v_mfma_f32_16x16x32_bf16 v[204:207], v[180:183], v[16:19], v[176:179]
	v_cndmask_b32_e32 v168, v147, v70, vcc
	v_fma_f32 v70, v170, s77, 0
	v_cmp_gt_u32_e32 vcc, s76, v71
	v_mfma_f32_16x16x32_bf16 v[174:177], v[188:191], v[8:11], v[208:211]
	v_add_u32_e32 v71, 0x1fcf, v2
	v_cndmask_b32_e32 v169, v147, v70, vcc
	v_fma_f32 v70, v171, s77, 0
	v_cmp_gt_u32_e32 vcc, s76, v71
	v_add_u32_e32 v71, 0x1fce, v2
	s_waitcnt lgkmcnt(0)
; DEVI float fast_exp2(float x) { return __builtin_amdgcn_exp2f(x); }
; DEVI void attn_item(const Params& p, int bg, int t0, unsigned char* smem) {
;     ...
;                         }
; #pragma unroll
;                         for (int ct = 0; ct < 2; ++ct) mr[ct] = rmax16(mr[ct]);
; #pragma unroll
;                         for (int ct = 0; ct < 2; ++ct) mr[ct] = rmax32(mr[ct]);
;                         bool need = false;
; #pragma unroll
;                         for (int ct = 0; ct < 2; ++ct) need = need || (fmaxf(m[ct], mr[ct]) - m[ct] > 8.0f);
;                         const bool resc = __builtin_amdgcn_ballot_w64(need) != 0;
; #pragma unroll
;                         for (int ct = 0; ct < 2; ++ct) {
;                             mn[ct] = resc ? fmaxf(m[ct], mr[ct]) : m[ct];
; #pragma unroll
;                             for (int mt = 0; mt < 4; ++mt)
; #pragma unroll
;                                 for (int rr = 0; rr < 4; ++rr) { s[ct][mt][rr] = fast_exp2(s[ct][mt][rr] - mn[ct]); }
;                         }
;                     } else {
; #pragma unroll
;                         for (int ct = 0; ct < 2; ++ct) {
;                             mr[ct] = fmaxf(fmaxf(s[ct][0][0], s[ct][0][1]), fmaxf(s[ct][0][2], s[ct][0][3]));
; #pragma unroll
;                             for (int mt = 1; mt < 4; ++mt) mr[ct] = fmaxf(mr[ct], fmaxf(fmaxf(s[ct][mt][0], s[ct][mt][1]), fmaxf(s[ct][mt][2], s[ct][mt][3])));
;                         }
; #pragma unroll
;                         for (int ct = 0; ct < 2; ++ct) mr[ct] = rmax16(mr[ct]);
; #pragma unroll
;                         for (int ct = 0; ct < 2; ++ct) mr[ct] = rmax32(mr[ct]);
;                         float cand[2];
;                         bool need = false;
; #pragma unroll
;                         for (int ct = 0; ct < 2; ++ct) {
;                             cand[ct] = fmaxf(m[ct], __builtin_fmaf(mr[ct], LOG2E, bias[ct]));
;                             need = need || (cand[ct] - m[ct] > 8.0f);
;                         }
;                         const bool resc = __builtin_amdgcn_ballot_w64(need) != 0;
; #pragma unroll
;                         for (int ct = 0; ct < 2; ++ct) {
;                             mn[ct] = resc ? cand[ct] : m[ct];
;                             const float nb = bias[ct] - mn[ct];
; #pragma unroll
;                             for (int mt = 0; mt < 4; ++mt)
; #pragma unroll
	v_mfma_f32_16x16x32_bf16 v[178:181], v[196:199], v[8:11], v[212:215]
	v_cndmask_b32_e32 v170, v147, v70, vcc
	v_fma_f32 v70, v172, s77, 0
	v_cmp_gt_u32_e32 vcc, s76, v71
	v_add_u32_e32 v71, 0x1fcd, v2
	v_mfma_f32_16x16x32_bf16 v[184:187], v[184:187], v[12:15], 0
	v_cndmask_b32_e32 v171, v147, v70, vcc
	v_fma_f32 v70, v173, s77, 0
	v_cmp_gt_u32_e32 vcc, s76, v71
	v_add_u32_e32 v71, 0x1fc0, v2
	v_add_u32_e32 v183, 0x1fe2, v2
	v_cndmask_b32_e32 v172, v147, v70, vcc
	v_fma_f32 v70, v174, s77, 0
	v_cmp_gt_u32_e32 vcc, s76, v71
	v_add_u32_e32 v71, 0x1fbf, v2
	v_mfma_f32_16x16x32_bf16 v[208:211], v[188:191], v[16:19], v[184:187]
	v_cndmask_b32_e32 v173, v147, v70, vcc
	v_fma_f32 v70, v175, s77, 0
	v_cmp_gt_u32_e32 vcc, s76, v71
	v_add_u32_e32 v71, 0x1fbe, v2
	v_add_u32_e32 v184, 0x1fe1, v2
	v_cndmask_b32_e32 v174, v147, v70, vcc
	v_fma_f32 v70, v176, s77, 0
	v_cmp_gt_u32_e32 vcc, s76, v71
	v_add_u32_e32 v71, 0x1fbd, v2
	v_add_u32_e32 v185, 0x1fd4, v2
	v_cndmask_b32_e32 v175, v147, v70, vcc
	v_fma_f32 v70, v177, s77, 0
	v_cmp_gt_u32_e32 vcc, s76, v71
	v_add_u32_e32 v71, 0x1fb0, v2
	v_mfma_f32_16x16x32_bf16 v[192:195], v[192:195], v[12:15], 0
	v_cndmask_b32_e32 v176, v147, v70, vcc
	v_fma_f32 v70, v178, s77, 0
	v_cmp_gt_u32_e32 vcc, s76, v71
	v_add_u32_e32 v71, 0x1faf, v2
	v_add_u32_e32 v186, 0x1fd3, v2
	v_cndmask_b32_e32 v177, v147, v70, vcc
	v_fma_f32 v70, v179, s77, 0
	v_cmp_gt_u32_e32 vcc, s76, v71
	v_add_u32_e32 v71, 0x1fae, v2
	v_add_u32_e32 v187, 0x1fd2, v2
	v_cndmask_b32_e32 v178, v147, v70, vcc
	v_fma_f32 v70, v180, s77, 0
	v_cmp_gt_u32_e32 vcc, s76, v71
	v_add_u32_e32 v71, 0x1fad, v2
	v_add_u32_e32 v188, 0x1fd1, v2
	v_cndmask_b32_e32 v179, v147, v70, vcc
	v_fma_f32 v70, v181, s77, 0
	v_cmp_gt_u32_e32 vcc, s76, v71
	v_add_u32_e32 v71, 0x1fe4, v2
	v_add_u32_e32 v189, 0x1fc4, v2
	v_cndmask_b32_e32 v180, v147, v70, vcc
	v_fma_f32 v70, v216, s77, 0
	v_cmp_gt_u32_e32 vcc, s76, v71
	v_add_u32_e32 v71, 0x1fe3, v2
	v_mfma_f32_16x16x32_bf16 v[194:197], v[196:199], v[16:19], v[192:195]
	v_cndmask_b32_e32 v181, v147, v70, vcc
	v_fma_f32 v70, v217, s77, 0
	v_cmp_gt_u32_e32 vcc, s76, v71
	v_fma_f32 v71, v218, s77, 0
	v_add_u32_e32 v190, 0x1fc3, v2
	v_cndmask_b32_e32 v182, v147, v70, vcc
	v_cmp_gt_u32_e32 vcc, s76, v183
	v_max3_f32 v0, v134, s78, v163
	v_add_u32_e32 v191, 0x1fc2, v2
	v_cndmask_b32_e32 v183, v147, v71, vcc
	v_fma_f32 v71, v219, s77, 0
	v_cmp_gt_u32_e32 vcc, s76, v184
	v_max3_f32 v0, v0, v167, v168
	v_max3_f32 v70, v181, s78, v182
	v_cndmask_b32_e32 v184, v147, v71, vcc
	v_fma_f32 v71, v204, s77, 0
	v_cmp_gt_u32_e32 vcc, s76, v185
	v_add_u32_e32 v192, 0x1fc1, v2
	v_max3_f32 v0, v0, v169, v170
	v_cndmask_b32_e32 v185, v147, v71, vcc
	v_fma_f32 v71, v205, s77, 0
	v_cmp_gt_u32_e32 vcc, s76, v186
	v_max3_f32 v70, v70, v183, v184
	v_add_u32_e32 v193, 0x1fb4, v2
	v_cndmask_b32_e32 v186, v147, v71, vcc
	v_fma_f32 v71, v206, s77, 0
	v_cmp_gt_u32_e32 vcc, s76, v187
	v_max3_f32 v0, v0, v171, v172
	v_max3_f32 v70, v70, v185, v186
	v_cndmask_b32_e32 v187, v147, v71, vcc
	v_fma_f32 v71, v207, s77, 0
	v_cmp_gt_u32_e32 vcc, s76, v188
	v_max3_f32 v0, v0, v173, v174
	v_max3_f32 v0, v0, v175, v176
	v_cndmask_b32_e32 v188, v147, v71, vcc
	v_fma_f32 v71, v208, s77, 0
	v_cmp_gt_u32_e32 vcc, s76, v189
	v_max3_f32 v70, v70, v187, v188
	v_max3_f32 v0, v0, v177, v178
	v_cndmask_b32_e32 v189, v147, v71, vcc
	v_fma_f32 v71, v209, s77, 0
	v_cmp_gt_u32_e32 vcc, s76, v190
	v_max3_f32 v0, v0, v179, v180
	s_nop 0
	v_cndmask_b32_e32 v190, v147, v71, vcc
	v_fma_f32 v71, v210, s77, 0
	v_cmp_gt_u32_e32 vcc, s76, v191
	v_max3_f32 v70, v70, v189, v190
	s_nop 0
	v_cndmask_b32_e32 v191, v147, v71, vcc
	v_fma_f32 v71, v211, s77, 0
	v_cmp_gt_u32_e32 vcc, s76, v192
	s_nop 1
	v_cndmask_b32_e32 v192, v147, v71, vcc
	v_fma_f32 v71, v194, s77, 0
	v_cmp_gt_u32_e32 vcc, s76, v193
	v_add_u32_e32 v194, 0x1fb3, v2
	v_max3_f32 v70, v70, v191, v192
	v_cndmask_b32_e32 v193, v147, v71, vcc
	v_fma_f32 v71, v195, s77, 0
	v_cmp_gt_u32_e32 vcc, s76, v194
	v_add_u32_e32 v195, 0x1fb2, v2
	v_add_u32_e32 v2, 0x1fb1, v2
	v_cndmask_b32_e32 v194, v147, v71, vcc
	v_fma_f32 v71, v196, s77, 0
	v_cmp_gt_u32_e32 vcc, s76, v195
	v_max3_f32 v70, v70, v193, v194
	s_nop 0
	v_cndmask_b32_e32 v195, v147, v71, vcc
	v_fma_f32 v71, v197, s77, 0
	v_cmp_gt_u32_e32 vcc, s76, v2
	s_nop 1
	v_cndmask_b32_e32 v196, v147, v71, vcc
	v_max3_f32 v2, v70, v195, v196
	v_mov_b32_e32 v70, v0
	s_nop 1
	v_permlane16_swap_b32_e32 v0, v70
	v_max_f32_e32 v70, v70, v70
	v_max_f32_e32 v0, v0, v0
	v_max_f32_e32 v0, v0, v70
	v_mov_b32_e32 v70, v2
	s_nop 1
	v_permlane16_swap_b32_e32 v2, v70
	v_max_f32_e32 v70, v70, v70
	v_max_f32_e32 v2, v2, v2
	v_max_f32_e32 v2, v2, v70
	v_mov_b32_e32 v70, v0
	v_mov_b32_e32 v71, v2
	s_nop 0
	v_permlane32_swap_b32_e32 v0, v70
	v_permlane32_swap_b32_e32 v2, v71
	v_max3_f32 v0, v130, v0, v70
	v_max3_f32 v2, v89, v2, v71
	v_sub_f32_e32 v70, v0, v130
	v_sub_f32_e32 v71, v2, v89
	v_max_f32_e32 v70, v70, v71
	v_cmp_lt_f32_e32 vcc, s16, v70
	s_cmp_eq_u64 vcc, 0
	s_cselect_b64 vcc, -1, 0
	v_cndmask_b32_e32 v70, v0, v130, vcc
	v_cndmask_b32_e32 v71, v2, v89, vcc
	v_sub_f32_e32 v0, v130, v70
	v_exp_f32_e32 v2, v0
	v_sub_f32_e32 v0, v89, v71
	v_exp_f32_e32 v0, v0
	v_cmp_neq_f32_e32 vcc, 1.0, v2
	v_cmp_neq_f32_e64 s[0:1], 1.0, v0
	s_or_b64 vcc, vcc, s[0:1]
	s_cbranch_vccz .LBB0_550
	v_pk_mul_f32 v[124:125], v[124:125], v[2:3] op_sel_hi:[1,0]
	v_pk_mul_f32 v[122:123], v[122:123], v[2:3] op_sel_hi:[1,0]
	v_pk_mul_f32 v[120:121], v[120:121], v[2:3] op_sel_hi:[1,0]
	v_pk_mul_f32 v[118:119], v[118:119], v[2:3] op_sel_hi:[1,0]
	v_pk_mul_f32 v[112:113], v[112:113], v[2:3] op_sel_hi:[1,0]
	v_pk_mul_f32 v[110:111], v[110:111], v[2:3] op_sel_hi:[1,0]
	v_pk_mul_f32 v[100:101], v[100:101], v[2:3] op_sel_hi:[1,0]
	v_pk_mul_f32 v[98:99], v[98:99], v[2:3] op_sel_hi:[1,0]
	v_pk_mul_f32 v[108:109], v[108:109], v[0:1] op_sel_hi:[1,0]
	v_pk_mul_f32 v[106:107], v[106:107], v[0:1] op_sel_hi:[1,0]
	v_pk_mul_f32 v[104:105], v[104:105], v[0:1] op_sel_hi:[1,0]
	v_pk_mul_f32 v[102:103], v[102:103], v[0:1] op_sel_hi:[1,0]
	v_pk_mul_f32 v[96:97], v[96:97], v[0:1] op_sel_hi:[1,0]
	v_pk_mul_f32 v[94:95], v[94:95], v[0:1] op_sel_hi:[1,0]
	v_pk_mul_f32 v[92:93], v[92:93], v[0:1] op_sel_hi:[1,0]
	v_pk_mul_f32 v[90:91], v[90:91], v[0:1] op_sel_hi:[1,0]
	v_pk_mul_f32 v[128:129], v[128:129], v[2:3] op_sel_hi:[1,0]
	v_pk_mul_f32 v[126:127], v[126:127], v[2:3] op_sel_hi:[1,0]
	v_pk_mul_f32 v[116:117], v[116:117], v[0:1] op_sel_hi:[1,0]
	v_pk_mul_f32 v[114:115], v[114:115], v[0:1] op_sel_hi:[1,0]

; DEVI void attn_item(const Params& p, int bg, int t0, unsigned char* smem) {
;     ...
;     auto tile_ptrs = [&](int n, const bf16_t*& kp, const bf16_t*& vp) {
;         if (n < n2) { const int c = n < n1 ? n : n - n1; kp = kc + (size_t)c * 4096; vp = vct + (size_t)c * 4096; }
;         else if (n < n3) { const int j = n - n2; kp = ksl + (size_t)j * 4096; vp = vsl + (size_t)j * 4096; }
;         else { const int j = jlo + (n - n3); kp = kwn + (size_t)j * 4096; vp = vwn + (size_t)j * 4096; }
;     ...
;     auto body = [&](auto kc, const int n) {
;         constexpr int KIND = decltype(kc)::value;
;         asm volatile("s_waitcnt vmcnt(0)\n\ts_barrier" ::: "memory");
;         if (n + 1 < ntot) {
;             const bf16_t *kp, *vp; tile_ptrs(n + 1, kp, vp);
;             glds_tile4(gv0, gv1, kp, vp, __builtin_amdgcn_readfirstlane(alds0 + ((n + 1) & 1) * 16384));
.LBB0_557:
	s_add_i32 s90, s92, 1
	s_cmp_lt_i32 s90, s22
	s_mov_b64 s[14:15], -1
	s_cbranch_scc1 .LBB0_559
	s_add_i32 s40, s91, 0x4000
	s_mov_b64 s[14:15], 0

; DEVI void attn_item(const Params& p, int bg, int t0, unsigned char* smem) {
;     ...
;         asm volatile("s_waitcnt vmcnt(0)\n\ts_barrier" ::: "memory");
;         if (n + 1 < ntot) {
;             const bf16_t *kp, *vp; tile_ptrs(n + 1, kp, vp);
;             glds_tile4(gv0, gv1, kp, vp, __builtin_amdgcn_readfirstlane(alds0 + ((n + 1) & 1) * 16384));
;         }
;         const unsigned char* cK = smem + (n & 1) * 16384;
;         const unsigned char* cV = cK + 8192;
;         constexpr bool is_p1 = KIND == 0, is_p2 = KIND == 1, is_slc = KIND == 2 || KIND == 4;
;         const int jt = is_slc ? n - n2 : jlo + (n - n3);
;         constexpr bool elem = KIND == 3 || KIND == 4;
;         const int wlim = is_slc ? 0x40000000 : 512;
;         const int c0 = (is_p1 ? n : n - n1) * 64;
;         bool any_act = true;
;         if (is_slc && !elem) {
;             const unsigned aw = __builtin_amdgcn_readfirstlane(anyw[jt >> 5] | anyw[4 + (jt >> 5)]);
;             any_act = (aw >> (jt & 31)) & 1u;
;         }
;         if (any_act) {
;             f32x4 s[2][4];
;             {
;                 bf16x8 k0[4], k1[4];
; #pragma unroll
;                 for (int mt = 0; mt < 4; ++mt) {
;                     k0[mt] = *(const bf16x8*)(cK + (mt * 16 + l16) * 128 + ((quad ^ rsw) * 16));
;                     k1[mt] = *(const bf16x8*)(cK + (mt * 16 + l16) * 128 + (((4 + quad) ^ rsw) * 16));
;                 }
; #pragma unroll
;                 for (int mt = 0; mt < 4; ++mt)
; #pragma unroll
;                     for (int ct = 0; ct < 2; ++ct) s[ct][mt] = mfma16(k0[mt], qf[ct][0], (f32x4){0.f, 0.f, 0.f, 0.f});
; #pragma unroll
;                 for (int mt = 0; mt < 4; ++mt)
; #pragma unroll
;                     for (int ct = 0; ct < 2; ++ct) s[ct][mt] = mfma16(k1[mt], qf[ct][1], s[ct][mt]);
;             }
;             if (is_p1) {
;                 float bm[2];
; #pragma unroll
;                 for (int ct = 0; ct < 2; ++ct) {
;                     bm[ct] = NINF;
; #pragma unroll
;                     for (int mt = 0; mt < 4; ++mt)
; #pragma unroll
;                         for (int rr = 0; rr < 4; ++rr) {
;                             const int c = c0 + mt * 16 + quad * 4 + rr;
;                             const float x = (16 * c + 31 <= tq[ct]) ? s[ct][mt][rr] * LOG2E : NINF;
;                             s[ct][mt][rr] = x; bm[ct] = fmaxf(bm[ct], x);
.LBB0_568:
	s_ashr_i32 s15, s14, 31
	s_lshl_b64 s[14:15], s[14:15], 13
	s_add_u32 s68, s68, s14
	s_addc_u32 s69, s69, s15
	s_add_u32 s14, s40, s14
	s_addc_u32 s15, s41, s15
	s_add_i32 s40, s91, 0x4000
	s_and_b32 s41, s40, 0x4000
	s_add_i32 s41, s41, s82
	s_waitcnt vmcnt(0)
	s_barrier
	s_mov_b32 s70, m0
	s_mov_b32 m0, s41
	s_nop 0
	global_load_lds_dwordx4 v158, s[68:69]
	s_add_u32 m0, m0, 0x1000
	s_nop 0
	global_load_lds_dwordx4 v159, s[68:69]
	s_add_u32 m0, m0, 0x1000
	s_nop 0
	global_load_lds_dwordx4 v158, s[14:15]
	s_add_u32 m0, m0, 0x1000
	s_nop 0
	global_load_lds_dwordx4 v159, s[14:15]
	s_mov_b32 m0, s70
	s_branch .LBB0_569
.Lawb_e:
	s_waitcnt vmcnt(0)
	s_barrier
.LBB0_569:
	s_and_b32 s14, s91, 0x4000
	v_or_b32_e32 v28, s14, v160
	v_add_u32_e32 v48, v28, v161
	ds_read_b128 v[24:27], v48
	v_add_u32_e32 v52, v28, v162
	ds_read_b128 v[28:31], v52
	ds_read_b128 v[32:35], v48 offset:2048
	ds_read_b128 v[36:39], v52 offset:2048
	ds_read_b128 v[40:43], v48 offset:4096
	ds_read_b128 v[44:47], v52 offset:4096
	ds_read_b128 v[48:51], v48 offset:6144
	ds_read_b128 v[52:55], v52 offset:6144
	s_waitcnt vmcnt(5) lgkmcnt(5)
	v_mfma_f32_16x16x32_bf16 v[60:63], v[32:35], v[4:7], 0
	s_cmp_lg_u32 s88, s90
	s_waitcnt vmcnt(2)
	v_mfma_f32_16x16x32_bf16 v[32:35], v[32:35], v[12:15], 0
	v_mfma_f32_16x16x32_bf16 v[56:59], v[24:27], v[4:7], 0
	v_mfma_f32_16x16x32_bf16 v[24:27], v[24:27], v[12:15], 0
	s_waitcnt lgkmcnt(3)
	v_mfma_f32_16x16x32_bf16 v[64:67], v[40:43], v[4:7], 0
	v_mfma_f32_16x16x32_bf16 v[40:43], v[40:43], v[12:15], 0
	s_waitcnt lgkmcnt(1)
	v_mfma_f32_16x16x32_bf16 v[68:71], v[48:51], v[4:7], 0
	v_mfma_f32_16x16x32_bf16 v[48:51], v[48:51], v[12:15], 0
	v_mfma_f32_16x16x32_bf16 v[56:59], v[28:31], v[8:11], v[56:59]
	s_waitcnt vmcnt(1)
	v_mfma_f32_16x16x32_bf16 v[24:27], v[28:31], v[16:19], v[24:27]
	v_mfma_f32_16x16x32_bf16 v[28:31], v[36:39], v[8:11], v[60:63]
	s_nop 4
	v_mul_f32_e32 v58, 0x3fb8aa3b, v58
	v_mul_f32_e32 v59, 0x3fb8aa3b, v59
	v_mul_f32_e32 v24, 0x3fb8aa3b, v24
	v_mfma_f32_16x16x32_bf16 v[32:35], v[36:39], v[16:19], v[32:35]
	v_add_u32_e32 v60, 0xfffffcf0, v2
	v_add_u32_e32 v61, 0xfffffd00, v2
	v_add_u32_e32 v62, 0xfffffdd0, v2
	v_mfma_f32_16x16x32_bf16 v[36:39], v[44:47], v[8:11], v[64:67]
	v_mul_f32_e32 v28, 0x3fb8aa3b, v28
	v_mul_f32_e32 v29, 0x3fb8aa3b, v29
	v_mul_f32_e32 v30, 0x3fb8aa3b, v30
	v_mfma_f32_16x16x32_bf16 v[40:43], v[44:47], v[16:19], v[40:43]
	v_add_u32_e32 v64, 0xfffffdf0, v2
	v_mul_f32_e32 v31, 0x3fb8aa3b, v31
	v_add_u32_e32 v66, 0xfffffed0, v2
	s_waitcnt lgkmcnt(0)
	v_mfma_f32_16x16x32_bf16 v[44:47], v[52:55], v[8:11], v[68:71]
	v_mul_f32_e32 v36, 0x3fb8aa3b, v36
	v_mul_f32_e32 v37, 0x3fb8aa3b, v37
	v_mul_f32_e32 v38, 0x3fb8aa3b, v38
	v_mfma_f32_16x16x32_bf16 v[48:51], v[52:55], v[16:19], v[48:51]
	v_add_u32_e32 v53, 0xfffffcd0, v2
	v_mul_f32_e32 v54, 0x3fb8aa3b, v56
	v_cmp_le_i32_e32 vcc, v53, v126
	v_add_u32_e32 v55, 0xfffffce0, v2
	v_mul_f32_e32 v56, 0x3fb8aa3b, v57
	v_cndmask_b32_e32 v54, v147, v54, vcc
	v_cmp_le_i32_e32 vcc, v55, v126
	v_add_u32_e32 v68, 0xfffffef0, v2
	v_subrev_u32_e32 v52, 48, v2
	v_cndmask_b32_e32 v56, v147, v56, vcc
	v_cmp_le_i32_e32 vcc, v60, v126
	v_mul_f32_e32 v39, 0x3fb8aa3b, v39
	v_mul_f32_e32 v44, 0x3fb8aa3b, v44
	v_cndmask_b32_e32 v58, v147, v58, vcc
	v_cmp_le_i32_e32 vcc, v61, v126
	v_max3_f32 v57, v54, s78, v56
	v_mul_f32_e32 v45, 0x3fb8aa3b, v45
	v_cndmask_b32_e32 v59, v147, v59, vcc
	v_cmp_le_i32_e32 vcc, v62, v126
	v_add_u32_e32 v71, -16, v2
	v_max3_f32 v57, v57, v58, v59
	v_cndmask_b32_e32 v63, v147, v28, vcc
	v_add_u32_e32 v28, 0xfffffde0, v2
	v_cmp_le_i32_e32 vcc, v28, v126
	v_mul_f32_e32 v46, 0x3fb8aa3b, v46
	v_mul_f32_e32 v26, 0x3fb8aa3b, v26
	v_cndmask_b32_e32 v29, v147, v29, vcc
	v_cmp_le_i32_e32 vcc, v64, v126
	v_max3_f32 v57, v57, v63, v29
	s_nop 0
	v_cndmask_b32_e32 v65, v147, v30, vcc
	v_add_u32_e32 v30, 0xfffffe00, v2
	v_cmp_le_i32_e32 vcc, v30, v126
	s_nop 1
	v_cndmask_b32_e32 v31, v147, v31, vcc
	v_cmp_le_i32_e32 vcc, v66, v126
	v_max3_f32 v57, v57, v65, v31
	s_nop 0
	v_cndmask_b32_e32 v67, v147, v36, vcc
	v_add_u32_e32 v36, 0xfffffee0, v2
	v_cmp_le_i32_e32 vcc, v36, v126
	s_nop 1
	v_cndmask_b32_e32 v37, v147, v37, vcc
	v_cmp_le_i32_e32 vcc, v68, v126
	v_max3_f32 v57, v57, v67, v37
	s_nop 0
	v_cndmask_b32_e32 v69, v147, v38, vcc
	v_add_u32_e32 v38, 0xffffff00, v2
	v_cmp_le_i32_e32 vcc, v38, v126
	s_nop 1
	v_cndmask_b32_e32 v39, v147, v39, vcc
	v_cmp_le_i32_e32 vcc, v52, v126
	v_max3_f32 v57, v57, v69, v39
	s_nop 0
	v_cndmask_b32_e32 v70, v147, v44, vcc
	v_subrev_u32_e32 v44, 32, v2
	v_cmp_le_i32_e32 vcc, v44, v126
	s_nop 1
	v_cndmask_b32_e32 v45, v147, v45, vcc
	v_cmp_le_i32_e32 vcc, v71, v126
	v_max3_f32 v57, v57, v70, v45
	s_nop 0
	v_cndmask_b32_e32 v72, v147, v46, vcc
	v_mul_f32_e32 v46, 0x3fb8aa3b, v47
	v_cmp_le_i32_e32 vcc, v2, v126
	s_nop 1
	v_cndmask_b32_e32 v47, v147, v46, vcc
	v_cmp_le_i32_e32 vcc, v53, v124
	v_max3_f32 v46, v57, v72, v47
	s_nop 0
	v_cndmask_b32_e32 v53, v147, v24, vcc
	v_mul_f32_e32 v24, 0x3fb8aa3b, v25
	v_cmp_le_i32_e32 vcc, v55, v124
	s_nop 1
	v_cndmask_b32_e32 v25, v147, v24, vcc
; DEVI float fast_exp2(float x) { return __builtin_amdgcn_exp2f(x); }
; DEVI float rmax16(float x) { const unsigned u = __float_as_uint(x); const auto r = __builtin_amdgcn_permlane16_swap(u, u, false, false); return fmaxf(__uint_as_float(r[0]), __uint_as_float(r[1])); }
; DEVI float rmax32(float x) { const unsigned u = __float_as_uint(x); const auto r = __builtin_amdgcn_permlane32_swap(u, u, false, false); return fmaxf(__uint_as_float(r[0]), __uint_as_float(r[1])); }
; DEVI void attn_item(const Params& p, int bg, int t0, unsigned char* smem) {
;     ...
;                             const int c = c0 + mt * 16 + quad * 4 + rr;
;                             const float x = (16 * c + 31 <= tq[ct]) ? s[ct][mt][rr] * LOG2E : NINF;
;                             s[ct][mt][rr] = x; bm[ct] = fmaxf(bm[ct], x);
;                         }
;                 }
; #pragma unroll
;                 for (int ct = 0; ct < 2; ++ct) bm[ct] = rmax16(bm[ct]);
; #pragma unroll
;                 for (int ct = 0; ct < 2; ++ct) bm[ct] = rmax32(bm[ct]);
; #pragma unroll
;                 for (int ct = 0; ct < 2; ++ct) {
;                     const float mn = fmaxf(m[ct], bm[ct]);
;                     float ls = 0.f;
; #pragma unroll
;                     for (int mt = 0; mt < 4; ++mt)
; #pragma unroll
;                         for (int rr = 0; rr < 4; ++rr) ls += fast_exp2(s[ct][mt][rr] - mn);
;                     lsum[ct] = lsum[ct] * fast_exp2(m[ct] - mn) + ls;
;                     m[ct] = mn;
;                 }
	v_cmp_le_i32_e32 vcc, v60, v124
	v_max3_f32 v24, v53, s78, v25
	s_nop 0
	v_cndmask_b32_e32 v55, v147, v26, vcc
	v_mul_f32_e32 v26, 0x3fb8aa3b, v27
	v_cmp_le_i32_e32 vcc, v61, v124
	s_nop 1
	v_cndmask_b32_e32 v57, v147, v26, vcc
	v_mul_f32_e32 v26, 0x3fb8aa3b, v32
	v_cmp_le_i32_e32 vcc, v62, v124
	v_max3_f32 v24, v24, v55, v57
	s_nop 0
	v_cndmask_b32_e32 v60, v147, v26, vcc
	v_mul_f32_e32 v26, 0x3fb8aa3b, v33
	v_cmp_le_i32_e32 vcc, v28, v124
	s_nop 1
	v_cndmask_b32_e32 v61, v147, v26, vcc
	v_mul_f32_e32 v26, 0x3fb8aa3b, v34
	v_cmp_le_i32_e32 vcc, v64, v124
	v_max3_f32 v24, v24, v60, v61
	s_nop 0
	v_cndmask_b32_e32 v62, v147, v26, vcc
	v_mul_f32_e32 v26, 0x3fb8aa3b, v35
	v_cmp_le_i32_e32 vcc, v30, v124
	s_nop 1
	v_cndmask_b32_e32 v64, v147, v26, vcc
	v_mul_f32_e32 v26, 0x3fb8aa3b, v40
	v_cmp_le_i32_e32 vcc, v66, v124
	v_max3_f32 v24, v24, v62, v64
	s_nop 0
	v_cndmask_b32_e32 v66, v147, v26, vcc
	v_mul_f32_e32 v26, 0x3fb8aa3b, v41
	v_cmp_le_i32_e32 vcc, v36, v124
	s_nop 1
	v_cndmask_b32_e32 v73, v147, v26, vcc
	v_mul_f32_e32 v26, 0x3fb8aa3b, v42
	v_cmp_le_i32_e32 vcc, v68, v124
	v_max3_f32 v24, v24, v66, v73
	s_nop 0
	v_cndmask_b32_e32 v68, v147, v26, vcc
	v_mul_f32_e32 v26, 0x3fb8aa3b, v43
	v_cmp_le_i32_e32 vcc, v38, v124
	s_nop 1
	v_cndmask_b32_e32 v74, v147, v26, vcc
	v_mul_f32_e32 v26, 0x3fb8aa3b, v48
	v_cmp_le_i32_e32 vcc, v52, v124
	v_max3_f32 v24, v24, v68, v74
	s_nop 0
	v_cndmask_b32_e32 v75, v147, v26, vcc
	v_mul_f32_e32 v26, 0x3fb8aa3b, v49
	v_cmp_le_i32_e32 vcc, v44, v124
	s_nop 1
	v_cndmask_b32_e32 v76, v147, v26, vcc
	v_mul_f32_e32 v26, 0x3fb8aa3b, v50
	v_cmp_le_i32_e32 vcc, v71, v124
	v_max3_f32 v24, v24, v75, v76
	s_nop 0
	v_cndmask_b32_e32 v71, v147, v26, vcc
	v_mul_f32_e32 v26, 0x3fb8aa3b, v51
	v_cmp_le_i32_e32 vcc, v2, v124
	v_add_u32_e32 v2, 0x400, v2
	s_nop 0
	v_cndmask_b32_e32 v77, v147, v26, vcc
	v_mov_b32_e32 v26, v46
	s_nop 1
	v_permlane16_swap_b32_e32 v46, v26
	v_max3_f32 v24, v24, v71, v77
	v_max_f32_e32 v26, v26, v26
	v_max_f32_e32 v27, v46, v46
	v_max_f32_e32 v26, v27, v26
	v_mov_b32_e32 v27, v24
	s_nop 1
	v_permlane16_swap_b32_e32 v24, v27
	v_max_f32_e32 v27, v27, v27
	v_max_f32_e32 v24, v24, v24
	v_max_f32_e32 v27, v24, v27
	v_mov_b32_e32 v24, v26
	s_nop 1
	v_permlane32_swap_b32_e32 v26, v24
	v_max3_f32 v24, v23, v26, v24
	v_sub_f32_e32 v29, v29, v24
	v_exp_f32_e32 v36, v29
	v_sub_f32_e32 v29, v65, v24
	v_exp_f32_e32 v38, v29
	v_sub_f32_e32 v29, v31, v24
	v_exp_f32_e32 v40, v29
	v_sub_f32_e32 v29, v67, v24
	v_exp_f32_e32 v42, v29
	v_sub_f32_e32 v29, v37, v24
	v_exp_f32_e32 v44, v29
	v_sub_f32_e32 v29, v69, v24
	v_mov_b32_e32 v33, v27
	v_exp_f32_e32 v46, v29
	v_sub_f32_e32 v29, v39, v24
	v_permlane32_swap_b32_e32 v27, v33
	v_exp_f32_e32 v48, v29
	v_sub_f32_e32 v29, v70, v24
	v_sub_f32_e32 v23, v23, v24
	v_sub_f32_e32 v30, v58, v24
	v_exp_f32_e32 v50, v29
	v_sub_f32_e32 v29, v45, v24
	v_exp_f32_e32 v58, v23
	v_max3_f32 v23, v22, v27, v33
	v_sub_f32_e32 v26, v54, v24
	v_exp_f32_e32 v52, v29
	v_sub_f32_e32 v29, v72, v24
	v_sub_f32_e32 v27, v53, v23
	v_exp_f32_e32 v26, v26
	v_sub_f32_e32 v28, v56, v24
	v_exp_f32_e32 v54, v29
	v_sub_f32_e32 v29, v47, v24
	v_exp_f32_e32 v27, v27
	v_sub_f32_e32 v25, v25, v23
	v_exp_f32_e32 v28, v28
	v_exp_f32_e32 v56, v29
	v_exp_f32_e32 v29, v25
	v_sub_f32_e32 v25, v55, v23
	v_exp_f32_e32 v30, v30
	v_sub_f32_e32 v32, v59, v24
	v_exp_f32_e32 v31, v25
	v_sub_f32_e32 v25, v57, v23
	v_exp_f32_e32 v32, v32
	v_sub_f32_e32 v34, v63, v24
	v_exp_f32_e32 v33, v25
	v_sub_f32_e32 v25, v60, v23
	v_exp_f32_e32 v34, v34
	v_exp_f32_e32 v35, v25
	v_sub_f32_e32 v25, v61, v23
	v_pk_add_f32 v[26:27], v[26:27], 0 op_sel_hi:[1,0]
	v_exp_f32_e32 v37, v25
	v_sub_f32_e32 v25, v62, v23
	v_pk_add_f32 v[26:27], v[28:29], v[26:27]
	v_exp_f32_e32 v39, v25
	v_sub_f32_e32 v25, v64, v23
	v_pk_add_f32 v[26:27], v[30:31], v[26:27]
	v_exp_f32_e32 v41, v25
	v_sub_f32_e32 v25, v66, v23
	v_pk_add_f32 v[26:27], v[32:33], v[26:27]
	v_exp_f32_e32 v43, v25
	v_sub_f32_e32 v25, v73, v23
	v_pk_add_f32 v[26:27], v[34:35], v[26:27]
	v_exp_f32_e32 v45, v25
	v_sub_f32_e32 v25, v68, v23
	v_pk_add_f32 v[26:27], v[36:37], v[26:27]
	v_exp_f32_e32 v47, v25
	v_pk_add_f32 v[26:27], v[38:39], v[26:27]
	v_sub_f32_e32 v25, v74, v23
	v_pk_add_f32 v[26:27], v[40:41], v[26:27]
	v_exp_f32_e32 v49, v25
	v_sub_f32_e32 v25, v75, v23
	v_pk_add_f32 v[26:27], v[42:43], v[26:27]
	v_exp_f32_e32 v51, v25
	v_sub_f32_e32 v25, v76, v23
	v_pk_add_f32 v[26:27], v[44:45], v[26:27]
	v_exp_f32_e32 v53, v25
	v_sub_f32_e32 v25, v71, v23
	v_pk_add_f32 v[26:27], v[46:47], v[26:27]
	v_exp_f32_e32 v55, v25
	v_sub_f32_e32 v25, v77, v23
	v_exp_f32_e32 v57, v25
	v_sub_f32_e32 v22, v22, v23
	v_pk_add_f32 v[26:27], v[48:49], v[26:27]
	v_exp_f32_e32 v59, v22
	v_pk_add_f32 v[26:27], v[50:51], v[26:27]
	s_nop 0
	v_pk_add_f32 v[26:27], v[52:53], v[26:27]
	s_nop 0
	v_pk_add_f32 v[26:27], v[54:55], v[26:27]
	s_nop 0
	v_pk_add_f32 v[26:27], v[56:57], v[26:27]
	s_nop 0
	v_pk_fma_f32 v[20:21], v[20:21], v[58:59], v[26:27]
	s_cbranch_scc0 .LBB0_572
	s_mov_b32 s91, s40
	v_mov_b32_e32 v22, v23
	v_mov_b32_e32 v23, v24
	s_mov_b32 s92, s90
	s_branch .LBB0_557

; DEVI void attn_item(const Params& p, int bg, int t0, unsigned char* smem) {
;     ...
;     auto tile_ptrs = [&](int n, const bf16_t*& kp, const bf16_t*& vp) {
;         if (n < n2) { const int c = n < n1 ? n : n - n1; kp = kc + (size_t)c * 4096; vp = vct + (size_t)c * 4096; }
;         else if (n < n3) { const int j = n - n2; kp = ksl + (size_t)j * 4096; vp = vsl + (size_t)j * 4096; }
;         else { const int j = jlo + (n - n3); kp = kwn + (size_t)j * 4096; vp = vwn + (size_t)j * 4096; }
;     ...
;     auto body = [&](auto kc, const int n) {
;         constexpr int KIND = decltype(kc)::value;
;         asm volatile("s_waitcnt vmcnt(0)\n\ts_barrier" ::: "memory");
;         if (n + 1 < ntot) {
;             const bf16_t *kp, *vp; tile_ptrs(n + 1, kp, vp);
;             glds_tile4(gv0, gv1, kp, vp, __builtin_amdgcn_readfirstlane(alds0 + ((n + 1) & 1) * 16384));
.LBB0_593:
	s_add_i32 s90, s13, 1
	s_cmp_ge_i32 s90, s22
	s_cbranch_scc1 .Lawb_f
	s_cmp_ge_u32 s90, s80
	s_mov_b64 s[70:71], -1
	s_cbranch_scc0 .LBB0_600
	s_cmp_ge_i32 s90, s81
	s_mov_b64 s[14:15], -1
	s_cbranch_scc0 .LBB0_597
	s_add_i32 s0, s89, s13
	s_mov_b64 s[14:15], 0

; DEVI float fast_exp2(float x) { return __builtin_amdgcn_exp2f(x); }
; DEVI void attn_item(const Params& p, int bg, int t0, unsigned char* smem) {
;     ...
;         asm volatile("s_waitcnt vmcnt(0)\n\ts_barrier" ::: "memory");
;         if (n + 1 < ntot) {
;             const bf16_t *kp, *vp; tile_ptrs(n + 1, kp, vp);
;             glds_tile4(gv0, gv1, kp, vp, __builtin_amdgcn_readfirstlane(alds0 + ((n + 1) & 1) * 16384));
;     ...
;                 if (is_p2) {
; #pragma unroll
;                     for (int ct = 0; ct < 2; ++ct) {
;                         const int q8 = ct * 4 + (l16 >> 2);
; #pragma unroll
;                         for (int mt = 0; mt < 4; ++mt) {
; #pragma unroll
;                             for (int rr = 0; rr < 4; ++rr) {
;                                 const int c = c0 + mt * 16 + quad * 4 + rr;
;                                 s[ct][mt][rr] = (16 * c + 31 <= tq[ct]) ? fast_exp2(s[ct][mt][rr] * LOG2E - m[ct]) * invl[ct] : 0.f;
;                             }
;                             float gs = (s[ct][mt][0] + s[ct][mt][1]) + (s[ct][mt][2] + s[ct][mt][3]);
;                             float es = s[ct][mt][3];
;                             gs += __int_as_float(__builtin_amdgcn_update_dpp(0, __float_as_int(gs), 0xB1, 0xf, 0xf, false));
;                             gs += __int_as_float(__builtin_amdgcn_update_dpp(0, __float_as_int(gs), 0x4E, 0xf, 0xf, false));
;                             es += __int_as_float(__builtin_amdgcn_update_dpp(0, __float_as_int(es), 0xB1, 0xf, 0xf, false));
;                             es += __int_as_float(__builtin_amdgcn_update_dpp(0, __float_as_int(es), 0x4E, 0xf, 0xf, false));
;                             if (r == 0) {
;                                 const int j = (c0 >> 2) + mt * 4 + quad;
;                                 imp[q8 * 128 + j] = gs;
;                                 impe[q8 * 128 + j] = es;
;                             }
;                         }
.LBB0_602:
	s_ashr_i32 s1, s0, 31
	s_lshl_b64 s[0:1], s[0:1], 13
	s_add_u32 s68, s68, s0
	s_addc_u32 s69, s69, s1
	s_add_u32 s0, s14, s0
	s_addc_u32 s1, s15, s1
	s_add_i32 s13, s88, 0x4000
	s_and_b32 s13, s13, 0x4000
	s_add_i32 s13, s13, s82
	s_waitcnt vmcnt(0)
	s_barrier
	s_mov_b32 s14, m0
	s_mov_b32 m0, s13
	s_nop 0
	global_load_lds_dwordx4 v158, s[68:69]
	s_add_u32 m0, m0, 0x1000
	s_nop 0
	global_load_lds_dwordx4 v159, s[68:69]
	s_add_u32 m0, m0, 0x1000
	s_nop 0
	global_load_lds_dwordx4 v158, s[0:1]
	s_add_u32 m0, m0, 0x1000
	s_nop 0
	global_load_lds_dwordx4 v159, s[0:1]
	s_mov_b32 m0, s14
	s_branch .LBB0_603
.Lawb_f:
	s_waitcnt vmcnt(0)
	s_barrier
.LBB0_603:
	s_and_b32 s0, s88, 0x4000
	v_or_b32_e32 v96, s0, v160
	v_add_u32_e32 v40, v96, v161
	ds_read_b128 v[20:23], v40
	v_add_u32_e32 v44, v96, v162
	ds_read_b128 v[24:27], v44
	ds_read_b128 v[28:31], v40 offset:2048
	ds_read_b128 v[36:39], v44 offset:2048
	ds_read_b128 v[32:35], v40 offset:4096
	ds_read_b128 v[98:101], v44 offset:4096
	ds_read_b128 v[40:43], v40 offset:6144
	ds_read_b128 v[102:105], v44 offset:6144
	s_waitcnt vmcnt(5) lgkmcnt(3)
	v_mfma_f32_16x16x32_bf16 v[110:113], v[32:35], v[4:7], 0
	v_or_b32_e32 v95, 47, v0
	v_cmp_le_i32_e32 vcc, v95, v51
	v_mov_b32_e32 v97, v0
	s_waitcnt vmcnt(2)
	v_mfma_f32_16x16x32_bf16 v[114:117], v[32:35], v[12:15], 0
	v_mfma_f32_16x16x32_bf16 v[44:47], v[20:23], v[4:7], 0
	v_mfma_f32_16x16x32_bf16 v[172:175], v[24:27], v[8:11], v[44:47]
	v_mfma_f32_16x16x32_bf16 v[20:23], v[20:23], v[12:15], 0
	s_waitcnt lgkmcnt(1)
	v_mfma_f32_16x16x32_bf16 v[118:121], v[40:43], v[4:7], 0
	s_nop 4
	v_fma_f32 v50, v172, s77, -v166
	v_mfma_f32_16x16x32_bf16 v[168:171], v[40:43], v[12:15], 0
	s_waitcnt vmcnt(1)
	v_mfma_f32_16x16x32_bf16 v[32:35], v[24:27], v[16:19], v[20:23]
	v_mfma_f32_16x16x32_bf16 v[40:43], v[98:101], v[8:11], v[110:113]
	v_mfma_f32_16x16x32_bf16 v[24:27], v[98:101], v[16:19], v[114:117]
	v_exp_f32_e32 v98, v50
	v_fma_f32 v50, v173, s77, -v166
	v_exp_f32_e32 v99, v50
	v_or_b32_e32 v50, 31, v0
	v_mfma_f32_16x16x32_bf16 v[106:109], v[28:31], v[4:7], 0
	v_mul_f32_e64 v100, v2, v98
	v_mul_f32_e64 v101, v3, v99
	v_cndmask_b32_e32 v98, 0, v101, vcc
	v_cmp_le_i32_e32 vcc, v50, v126
	v_fma_f32 v101, v175, s77, -v166
	v_exp_f32_e32 v101, v101
	v_cndmask_b32_e32 v99, 0, v100, vcc
	v_fma_f32 v100, v174, s77, -v166
	v_exp_f32_e32 v100, v100
	v_mfma_f32_16x16x32_bf16 v[28:31], v[28:31], v[12:15], 0
	v_mul_f32_e32 v101, v2, v101
	v_mul_f32_e32 v100, v2, v100
	v_mfma_f32_16x16x32_bf16 v[44:47], v[36:39], v[8:11], v[106:109]
	s_nop 2
	v_add_u32_e32 v107, 63, v0
	v_cmp_le_i32_e32 vcc, v107, v126
	v_add_u32_e32 v108, 0x4f, v0
	v_mfma_f32_16x16x32_bf16 v[28:31], v[36:39], v[16:19], v[28:31]
	v_cndmask_b32_e32 v100, 0, v100, vcc
	v_cmp_le_i32_e32 vcc, v108, v126
	s_waitcnt lgkmcnt(0)
	v_mfma_f32_16x16x32_bf16 v[36:39], v[102:105], v[8:11], v[118:121]
	v_cndmask_b32_e32 v101, 0, v101, vcc
	v_mfma_f32_16x16x32_bf16 v[20:23], v[102:105], v[16:19], v[168:171]
	v_add_f32_e32 v102, v99, v98
	v_add_f32_e32 v103, v100, v101
	v_add_f32_e32 v102, v102, v103
	v_mov_b32_e32 v103, 0
	v_add_f32_dpp v104, v101, v101 quad_perm:[1,0,3,2] row_mask:0xf bank_mask:0xf bound_ctrl:1
	v_add_f32_dpp v102, v102, v102 quad_perm:[1,0,3,2] row_mask:0xf bank_mask:0xf bound_ctrl:1
	v_mov_b32_e32 v105, 0
	s_nop 0
	v_mov_b32_dpp v103, v102 quad_perm:[2,3,0,1] row_mask:0xf bank_mask:0xf
	v_mov_b32_dpp v105, v104 quad_perm:[2,3,0,1] row_mask:0xf bank_mask:0xf
	s_and_saveexec_b64 s[0:1], s[40:41]
	v_add_f32_e32 v102, v102, v103
	v_add_f32_e32 v103, v104, v105
	ds_write2st64_b32 v94, v102, v103 offset1:16
	s_or_b64 exec, exec, s[0:1]
	v_fma_f32 v44, v44, s77, -v166
	v_exp_f32_e32 v102, v44
	v_fma_f32 v44, v45, s77, -v166
	v_exp_f32_e32 v103, v44
	v_fma_f32 v46, v46, s77, -v166
	v_exp_f32_e32 v46, v46
	v_fma_f32 v47, v47, s77, -v166
	v_or_b32_e32 v45, 0x12f, v97
	v_exp_f32_e32 v47, v47
	v_or_b32_e32 v44, 0x11f, v0
	v_pk_mul_f32 v[104:105], v[2:3], v[102:103]
	v_cmp_le_i32_e32 vcc, v45, v51
	v_add_u32_e32 v109, 0x13f, v0
	v_mul_f32_e32 v46, v2, v46
	v_cndmask_b32_e32 v102, 0, v105, vcc
	v_cmp_le_i32_e32 vcc, v44, v126
	v_add_u32_e32 v111, 0x14f, v0
	v_mov_b32_e32 v112, 0
	v_cndmask_b32_e32 v103, 0, v104, vcc
	v_cmp_le_i32_e32 vcc, v109, v126
	v_add_u32_e32 v110, 16, v94
	s_nop 0
	v_cndmask_b32_e32 v104, 0, v46, vcc
	v_mul_f32_e32 v46, v2, v47
	v_cmp_le_i32_e32 vcc, v111, v126
	s_nop 1
	v_cndmask_b32_e32 v105, 0, v46, vcc
	v_add_f32_e32 v46, v103, v102
	v_add_f32_e32 v47, v104, v105
	v_add_f32_e32 v46, v46, v47
	v_mov_b32_e32 v47, 0
	v_add_f32_dpp v106, v105, v105 quad_perm:[1,0,3,2] row_mask:0xf bank_mask:0xf bound_ctrl:1
	v_add_f32_dpp v46, v46, v46 quad_perm:[1,0,3,2] row_mask:0xf bank_mask:0xf bound_ctrl:1
	s_nop 0
	v_mov_b32_dpp v112, v106 quad_perm:[2,3,0,1] row_mask:0xf bank_mask:0xf
	v_mov_b32_dpp v47, v46 quad_perm:[2,3,0,1] row_mask:0xf bank_mask:0xf
	s_and_saveexec_b64 s[0:1], s[40:41]
	v_add_f32_e32 v46, v46, v47
	v_add_f32_e32 v47, v106, v112
	ds_write2st64_b32 v110, v46, v47 offset1:16
	s_or_b64 exec, exec, s[0:1]
	v_fma_f32 v40, v40, s77, -v166
	v_exp_f32_e32 v46, v40
	v_fma_f32 v40, v41, s77, -v166
	v_exp_f32_e32 v47, v40
	v_fma_f32 v42, v42, s77, -v166
	v_or_b32_e32 v41, 0x22f, v97
	v_fma_f32 v43, v43, s77, -v166
	v_pk_mul_f32 v[112:113], v[2:3], v[46:47]
	v_exp_f32_e32 v47, v42
	v_or_b32_e32 v40, 0x21f, v0
	v_cmp_le_i32_e32 vcc, v41, v51
	v_exp_f32_e32 v106, v43
	v_mul_f32_e32 v47, v2, v47
	v_cndmask_b32_e32 v46, 0, v113, vcc
	v_cmp_le_i32_e32 vcc, v40, v126
	v_add_u32_e32 v114, 0x24f, v0
	v_mov_b32_e32 v115, 0
	v_cndmask_b32_e32 v42, 0, v112, vcc
	v_add_u32_e32 v112, 0x23f, v0
; DEVI float fast_exp2(float x) { return __builtin_amdgcn_exp2f(x); }
; DEVI void attn_item(const Params& p, int bg, int t0, unsigned char* smem) {
;     ...
;                     for (int ct = 0; ct < 2; ++ct) {
;                         const int q8 = ct * 4 + (l16 >> 2);
; #pragma unroll
;                         for (int mt = 0; mt < 4; ++mt) {
; #pragma unroll
;                             for (int rr = 0; rr < 4; ++rr) {
;                                 const int c = c0 + mt * 16 + quad * 4 + rr;
;                                 s[ct][mt][rr] = (16 * c + 31 <= tq[ct]) ? fast_exp2(s[ct][mt][rr] * LOG2E - m[ct]) * invl[ct] : 0.f;
;                             }
;                             float gs = (s[ct][mt][0] + s[ct][mt][1]) + (s[ct][mt][2] + s[ct][mt][3]);
;                             float es = s[ct][mt][3];
;                             gs += __int_as_float(__builtin_amdgcn_update_dpp(0, __float_as_int(gs), 0xB1, 0xf, 0xf, false));
;                             gs += __int_as_float(__builtin_amdgcn_update_dpp(0, __float_as_int(gs), 0x4E, 0xf, 0xf, false));
;                             es += __int_as_float(__builtin_amdgcn_update_dpp(0, __float_as_int(es), 0xB1, 0xf, 0xf, false));
;                             es += __int_as_float(__builtin_amdgcn_update_dpp(0, __float_as_int(es), 0x4E, 0xf, 0xf, false));
;                             if (r == 0) {
;                                 const int j = (c0 >> 2) + mt * 4 + quad;
;                                 imp[q8 * 128 + j] = gs;
;                                 impe[q8 * 128 + j] = es;
;                             }
;                         }
	v_cmp_le_i32_e32 vcc, v112, v126
	v_mov_b32_e32 v117, 0
	s_nop 0
	v_cndmask_b32_e32 v43, 0, v47, vcc
	v_mul_f32_e32 v47, v2, v106
	v_cmp_le_i32_e32 vcc, v114, v126
	v_add_f32_e32 v106, v42, v46
	s_nop 0
	v_cndmask_b32_e32 v47, 0, v47, vcc
	v_add_f32_e32 v113, v43, v47
	v_add_f32_e32 v106, v106, v113
	v_add_f32_dpp v116, v47, v47 quad_perm:[1,0,3,2] row_mask:0xf bank_mask:0xf bound_ctrl:1
	v_add_u32_e32 v113, 32, v94
	v_add_f32_dpp v106, v106, v106 quad_perm:[1,0,3,2] row_mask:0xf bank_mask:0xf bound_ctrl:1
	v_mov_b32_dpp v117, v116 quad_perm:[2,3,0,1] row_mask:0xf bank_mask:0xf
	s_nop 0
	v_mov_b32_dpp v115, v106 quad_perm:[2,3,0,1] row_mask:0xf bank_mask:0xf
	s_and_saveexec_b64 s[0:1], s[40:41]
	v_add_f32_e32 v106, v106, v115
	v_add_f32_e32 v115, v116, v117
	ds_write2st64_b32 v113, v106, v115 offset1:16
	s_or_b64 exec, exec, s[0:1]
	v_fma_f32 v36, v36, s77, -v166
	v_exp_f32_e32 v116, v36
	v_fma_f32 v36, v37, s77, -v166
	v_exp_f32_e32 v117, v36
	v_or_b32_e32 v37, 0x32f, v97
	v_or_b32_e32 v36, 0x31f, v0
	v_cmp_le_i32_e32 vcc, v37, v51
	v_pk_mul_f32 v[116:117], v[2:3], v[116:117]
	v_fma_f32 v38, v38, s77, -v166
	v_cndmask_b32_e32 v97, 0, v117, vcc
	v_exp_f32_e32 v106, v38
	v_cmp_le_i32_e32 vcc, v36, v126
	v_fma_f32 v39, v39, s77, -v166
	v_add_u32_e32 v115, 0x33f, v0
	v_cndmask_b32_e32 v38, 0, v116, vcc
	v_exp_f32_e32 v116, v39
	v_mul_f32_e32 v106, v2, v106
	v_cmp_le_i32_e32 vcc, v115, v126
	v_add_u32_e32 v117, 0x34f, v0
	v_mov_b32_e32 v119, 0
	v_cndmask_b32_e32 v39, 0, v106, vcc
	v_mul_f32_e32 v106, v2, v116
	v_cmp_le_i32_e32 vcc, v117, v126
	v_add_f32_e32 v116, v38, v97
	v_mov_b32_e32 v121, 0
	v_cndmask_b32_e32 v106, 0, v106, vcc
	v_add_f32_e32 v118, v39, v106
	v_add_f32_e32 v116, v116, v118
	v_add_f32_dpp v120, v106, v106 quad_perm:[1,0,3,2] row_mask:0xf bank_mask:0xf bound_ctrl:1
	s_nop 0
	v_add_f32_dpp v118, v116, v116 quad_perm:[1,0,3,2] row_mask:0xf bank_mask:0xf bound_ctrl:1
	v_mov_b32_dpp v121, v120 quad_perm:[2,3,0,1] row_mask:0xf bank_mask:0xf
	v_add_u32_e32 v116, 48, v94
	v_mov_b32_dpp v119, v118 quad_perm:[2,3,0,1] row_mask:0xf bank_mask:0xf
	s_and_saveexec_b64 s[0:1], s[40:41]
	v_add_f32_e32 v118, v118, v119
	v_add_f32_e32 v119, v120, v121
	ds_write2st64_b32 v116, v118, v119 offset1:16
	s_or_b64 exec, exec, s[0:1]
	v_fma_f32 v32, v32, s77, -v165
	v_fma_f32 v33, v33, s77, -v165
	v_exp_f32_e32 v32, v32
	v_exp_f32_e32 v33, v33
	v_fma_f32 v35, v35, s77, -v165
	v_exp_f32_e32 v35, v35
	v_cmp_le_i32_e32 vcc, v95, v93
	v_pk_mul_f32 v[118:119], v[48:49], v[32:33]
	v_fma_f32 v33, v34, s77, -v165
	v_exp_f32_e32 v34, v33
	v_cndmask_b32_e32 v32, 0, v119, vcc
	v_cmp_le_i32_e32 vcc, v50, v124
	v_mul_f32_e32 v35, v48, v35
	v_mul_f32_e32 v34, v48, v34
	v_cndmask_b32_e32 v33, 0, v118, vcc
	v_cmp_le_i32_e32 vcc, v107, v124
	v_add_f32_e32 v50, v33, v32
	s_nop 0
	v_cndmask_b32_e32 v34, 0, v34, vcc
	v_cmp_le_i32_e32 vcc, v108, v124
	v_mov_b32_e32 v108, 0
	s_nop 0
	v_cndmask_b32_e32 v35, 0, v35, vcc
	v_add_f32_e32 v95, v34, v35
	v_add_f32_e32 v50, v50, v95
	v_mov_b32_e32 v95, 0
	v_add_f32_dpp v107, v35, v35 quad_perm:[1,0,3,2] row_mask:0xf bank_mask:0xf bound_ctrl:1
	v_add_f32_dpp v50, v50, v50 quad_perm:[1,0,3,2] row_mask:0xf bank_mask:0xf bound_ctrl:1
	s_nop 0
	v_mov_b32_dpp v108, v107 quad_perm:[2,3,0,1] row_mask:0xf bank_mask:0xf
	v_mov_b32_dpp v95, v50 quad_perm:[2,3,0,1] row_mask:0xf bank_mask:0xf
	s_and_saveexec_b64 s[0:1], s[40:41]
	v_add_f32_e32 v50, v50, v95
	v_add_f32_e32 v95, v107, v108
	ds_write2st64_b32 v94, v50, v95 offset0:8 offset1:24
	s_or_b64 exec, exec, s[0:1]
	v_fma_f32 v28, v28, s77, -v165
	v_fma_f32 v29, v29, s77, -v165
	v_exp_f32_e32 v28, v28
	v_exp_f32_e32 v29, v29
; DEVI float fast_exp2(float x) { return __builtin_amdgcn_exp2f(x); }
; DEVI void attn_item(const Params& p, int bg, int t0, unsigned char* smem) {
;     ...
;                     for (int ct = 0; ct < 2; ++ct) {
;                         const int q8 = ct * 4 + (l16 >> 2);
; #pragma unroll
;                         for (int mt = 0; mt < 4; ++mt) {
; #pragma unroll
;                             for (int rr = 0; rr < 4; ++rr) {
;                                 const int c = c0 + mt * 16 + quad * 4 + rr;
;                                 s[ct][mt][rr] = (16 * c + 31 <= tq[ct]) ? fast_exp2(s[ct][mt][rr] * LOG2E - m[ct]) * invl[ct] : 0.f;
;                             }
;                             float gs = (s[ct][mt][0] + s[ct][mt][1]) + (s[ct][mt][2] + s[ct][mt][3]);
;                             float es = s[ct][mt][3];
;                             gs += __int_as_float(__builtin_amdgcn_update_dpp(0, __float_as_int(gs), 0xB1, 0xf, 0xf, false));
;                             gs += __int_as_float(__builtin_amdgcn_update_dpp(0, __float_as_int(gs), 0x4E, 0xf, 0xf, false));
;                             es += __int_as_float(__builtin_amdgcn_update_dpp(0, __float_as_int(es), 0xB1, 0xf, 0xf, false));
;                             es += __int_as_float(__builtin_amdgcn_update_dpp(0, __float_as_int(es), 0x4E, 0xf, 0xf, false));
;                             if (r == 0) {
;                                 const int j = (c0 >> 2) + mt * 4 + quad;
;                                 imp[q8 * 128 + j] = gs;
;                                 impe[q8 * 128 + j] = es;
;                             }
;                         }
	v_fma_f32 v31, v31, s77, -v165
	v_exp_f32_e32 v31, v31
	v_cmp_le_i32_e32 vcc, v45, v93
	v_pk_mul_f32 v[118:119], v[48:49], v[28:29]
	v_fma_f32 v29, v30, s77, -v165
	v_exp_f32_e32 v30, v29
	v_cndmask_b32_e32 v28, 0, v119, vcc
	v_cmp_le_i32_e32 vcc, v44, v124
	v_mul_f32_e32 v31, v48, v31
	v_mul_f32_e32 v30, v48, v30
	v_cndmask_b32_e32 v29, 0, v118, vcc
	v_cmp_le_i32_e32 vcc, v109, v124
	v_add_f32_e32 v44, v29, v28
	v_mov_b32_e32 v95, 0
	v_cndmask_b32_e32 v30, 0, v30, vcc
	v_cmp_le_i32_e32 vcc, v111, v124
	s_nop 1
	v_cndmask_b32_e32 v31, 0, v31, vcc
	v_add_f32_e32 v45, v30, v31
	v_add_f32_e32 v44, v44, v45
	v_mov_b32_e32 v45, 0
	v_add_f32_dpp v50, v31, v31 quad_perm:[1,0,3,2] row_mask:0xf bank_mask:0xf bound_ctrl:1
	v_add_f32_dpp v44, v44, v44 quad_perm:[1,0,3,2] row_mask:0xf bank_mask:0xf bound_ctrl:1
	s_nop 0
	v_mov_b32_dpp v95, v50 quad_perm:[2,3,0,1] row_mask:0xf bank_mask:0xf
	v_mov_b32_dpp v45, v44 quad_perm:[2,3,0,1] row_mask:0xf bank_mask:0xf
	s_and_saveexec_b64 s[0:1], s[40:41]
	v_add_f32_e32 v44, v44, v45
	v_add_f32_e32 v45, v50, v95
	ds_write2st64_b32 v110, v44, v45 offset0:8 offset1:24
	s_or_b64 exec, exec, s[0:1]
	v_fma_f32 v24, v24, s77, -v165
	v_fma_f32 v25, v25, s77, -v165
	v_exp_f32_e32 v24, v24
	v_exp_f32_e32 v25, v25
	v_fma_f32 v27, v27, s77, -v165
	v_exp_f32_e32 v27, v27
	v_cmp_le_i32_e32 vcc, v41, v93
	v_pk_mul_f32 v[44:45], v[48:49], v[24:25]
	v_fma_f32 v25, v26, s77, -v165
	v_exp_f32_e32 v26, v25
	v_cndmask_b32_e32 v24, 0, v45, vcc
	v_cmp_le_i32_e32 vcc, v40, v124
	v_mul_f32_e32 v27, v48, v27
	v_mul_f32_e32 v26, v48, v26
	v_cndmask_b32_e32 v25, 0, v44, vcc
	v_cmp_le_i32_e32 vcc, v112, v124
	v_add_f32_e32 v40, v25, v24
	v_mov_b32_e32 v45, 0
	v_cndmask_b32_e32 v26, 0, v26, vcc
	v_cmp_le_i32_e32 vcc, v114, v124
	s_nop 1
	v_cndmask_b32_e32 v27, 0, v27, vcc
	v_add_f32_e32 v41, v26, v27
	v_add_f32_e32 v40, v40, v41
	v_mov_b32_e32 v41, 0
	v_add_f32_dpp v44, v27, v27 quad_perm:[1,0,3,2] row_mask:0xf bank_mask:0xf bound_ctrl:1
	v_add_f32_dpp v40, v40, v40 quad_perm:[1,0,3,2] row_mask:0xf bank_mask:0xf bound_ctrl:1
	s_nop 0
	v_mov_b32_dpp v45, v44 quad_perm:[2,3,0,1] row_mask:0xf bank_mask:0xf
	v_mov_b32_dpp v41, v40 quad_perm:[2,3,0,1] row_mask:0xf bank_mask:0xf
	s_and_saveexec_b64 s[0:1], s[40:41]
	v_add_f32_e32 v40, v40, v41
	v_add_f32_e32 v41, v44, v45
	ds_write2st64_b32 v113, v40, v41 offset0:8 offset1:24
	s_or_b64 exec, exec, s[0:1]
	v_fma_f32 v20, v20, s77, -v165
	v_fma_f32 v21, v21, s77, -v165
	v_exp_f32_e32 v20, v20
	v_exp_f32_e32 v21, v21
	v_fma_f32 v23, v23, s77, -v165
	v_exp_f32_e32 v23, v23
	v_cmp_le_i32_e32 vcc, v37, v93
	v_pk_mul_f32 v[40:41], v[48:49], v[20:21]
	v_fma_f32 v21, v22, s77, -v165
	v_exp_f32_e32 v22, v21
	v_cndmask_b32_e32 v20, 0, v41, vcc
	v_cmp_le_i32_e32 vcc, v36, v124
	v_mul_f32_e32 v23, v48, v23
	v_mul_f32_e32 v22, v48, v22
	v_cndmask_b32_e32 v21, 0, v40, vcc
	v_cmp_le_i32_e32 vcc, v115, v124
	v_add_f32_e32 v36, v21, v20
	v_mov_b32_e32 v41, 0
	v_cndmask_b32_e32 v22, 0, v22, vcc
	v_cmp_le_i32_e32 vcc, v117, v124
	s_nop 1
	v_cndmask_b32_e32 v23, 0, v23, vcc
	v_add_f32_e32 v37, v22, v23
	v_add_f32_e32 v36, v36, v37
	v_mov_b32_e32 v37, 0
	v_add_f32_dpp v40, v23, v23 quad_perm:[1,0,3,2] row_mask:0xf bank_mask:0xf bound_ctrl:1
	v_add_f32_dpp v36, v36, v36 quad_perm:[1,0,3,2] row_mask:0xf bank_mask:0xf bound_ctrl:1
	s_nop 0
	v_mov_b32_dpp v41, v40 quad_perm:[2,3,0,1] row_mask:0xf bank_mask:0xf
	v_mov_b32_dpp v37, v36 quad_perm:[2,3,0,1] row_mask:0xf bank_mask:0xf
	s_and_saveexec_b64 s[0:1], s[40:41]
	s_cbranch_execz .LBB0_592
	v_add_f32_e32 v36, v36, v37
	v_add_f32_e32 v37, v40, v41
	ds_write2st64_b32 v116, v36, v37 offset0:8 offset1:24
	s_branch .LBB0_592

; DEVI void attn_item(const Params& p, int bg, int t0, unsigned char* smem) {
;     ...
;     auto tile_ptrs = [&](int n, const bf16_t*& kp, const bf16_t*& vp) {
;         if (n < n2) { const int c = n < n1 ? n : n - n1; kp = kc + (size_t)c * 4096; vp = vct + (size_t)c * 4096; }
;         else if (n < n3) { const int j = n - n2; kp = ksl + (size_t)j * 4096; vp = vsl + (size_t)j * 4096; }
;         else { const int j = jlo + (n - n3); kp = kwn + (size_t)j * 4096; vp = vwn + (size_t)j * 4096; }
;     ...
;     auto body = [&](auto kc, const int n) {
;         constexpr int KIND = decltype(kc)::value;
;         asm volatile("s_waitcnt vmcnt(0)\n\ts_barrier" ::: "memory");
;         if (n + 1 < ntot) {
;             const bf16_t *kp, *vp; tile_ptrs(n + 1, kp, vp);
;             glds_tile4(gv0, gv1, kp, vp, __builtin_amdgcn_readfirstlane(alds0 + ((n + 1) & 1) * 16384));
.LBB0_641:
	s_add_i32 s88, s13, 1
	s_cmp_ge_i32 s88, s22
	s_cbranch_scc1 .Lawb_g
	s_cmp_ge_u32 s88, s80
	s_mov_b64 s[68:69], -1
	s_cbranch_scc0 .LBB0_648
	s_cmp_ge_i32 s88, s81
	s_mov_b64 s[14:15], -1
	s_cbranch_scc0 .LBB0_645
	s_add_i32 s0, s90, s13
	s_mov_b64 s[14:15], 0

; DEVI void attn_item(const Params& p, int bg, int t0, unsigned char* smem) {
;     ...
;         if (is_slc && !elem) {
;             const unsigned aw = __builtin_amdgcn_readfirstlane(anyw[jt >> 5] | anyw[4 + (jt >> 5)]);
;             any_act = (aw >> (jt & 31)) & 1u;
;         }
;         if (any_act) {
;             f32x4 s[2][4];
;             {
;                 bf16x8 k0[4], k1[4];
; #pragma unroll
;                 for (int mt = 0; mt < 4; ++mt) {
;                     k0[mt] = *(const bf16x8*)(cK + (mt * 16 + l16) * 128 + ((quad ^ rsw) * 16));
;                     k1[mt] = *(const bf16x8*)(cK + (mt * 16 + l16) * 128 + (((4 + quad) ^ rsw) * 16));
;                 }
; #pragma unroll
;                 for (int mt = 0; mt < 4; ++mt)
; #pragma unroll
;                     for (int ct = 0; ct < 2; ++ct) s[ct][mt] = mfma16(k0[mt], qf[ct][0], (f32x4){0.f, 0.f, 0.f, 0.f});
; #pragma unroll
;                 for (int mt = 0; mt < 4; ++mt)
; #pragma unroll
;                     for (int ct = 0; ct < 2; ++ct) s[ct][mt] = mfma16(k1[mt], qf[ct][1], s[ct][mt]);
;     ...
;                         for (int ct = 0; ct < 2; ++ct) mr[ct] = rmax16(mr[ct]);
; #pragma unroll
;                         for (int ct = 0; ct < 2; ++ct) mr[ct] = rmax32(mr[ct]);
;                         float cand[2];
;                         bool need = false;
; #pragma unroll
;                         for (int ct = 0; ct < 2; ++ct) {
;                             cand[ct] = fmaxf(m[ct], __builtin_fmaf(mr[ct], LOG2E, bias[ct]));
;                             need = need || (cand[ct] - m[ct] > 8.0f);
;                         }
;                         const bool resc = __builtin_amdgcn_ballot_w64(need) != 0;
; #pragma unroll
;                         for (int ct = 0; ct < 2; ++ct) {
;                             mn[ct] = resc ? cand[ct] : m[ct];
;                             const float nb = bias[ct] - mn[ct];
; #pragma unroll
;                             for (int mt = 0; mt < 4; ++mt)
; #pragma unroll
;                                 for (int rr = 0; rr < 4; ++rr) { s[ct][mt][rr] = fast_exp2(__builtin_fmaf(s[ct][mt][rr], LOG2E, nb)); }
;                         }
;                     }
;                     float al[2];
; #pragma unroll
;                     for (int ct = 0; ct < 2; ++ct) {
;                         al[ct] = fast_exp2(m[ct] - mn[ct]);
;                         m[ct] = mn[ct];
.Lawb_g:
	s_waitcnt vmcnt(0)
	s_barrier
.LBB0_651:
	s_add_i32 s0, s70, s13
	s_ashr_i32 s1, s0, 5
	s_lshl_b32 s13, s1, 2
	s_add_i32 s13, s11, s13
	v_mov_b32_e32 v0, s13
	v_add_u32_e32 v0, 0xa000, v0
	ds_read2_b32 v[92:93], v0 offset0:32 offset1:36
	s_lshl_b32 s0, 1, s0
	s_waitcnt lgkmcnt(0)
	v_or_b32_e32 v0, v93, v92
	s_nop 0
	v_readfirstlane_b32 s13, v0
	s_and_b32 s13, s13, s0
	s_cmp_eq_u32 s13, 0
	s_cbranch_scc1 .LBB0_639
	s_and_b32 s13, s71, 0x4000
	v_or_b32_e32 v171, s13, v160
	v_add_u32_e32 v0, v171, v161
	ds_read_b128 v[92:95], v0
	v_add_u32_e32 v2, v171, v162
	ds_read_b128 v[96:99], v2
	ds_read_b128 v[100:103], v0 offset:2048
	ds_read_b128 v[108:111], v2 offset:2048
	ds_read_b128 v[104:107], v0 offset:4096
	ds_read_b128 v[172:175], v2 offset:4096
	ds_read_b128 v[112:115], v0 offset:6144
	ds_read_b128 v[176:179], v2 offset:6144
	s_waitcnt vmcnt(5) lgkmcnt(3)
	v_mfma_f32_16x16x32_bf16 v[184:187], v[104:107], v[4:7], 0
	v_lshl_add_u32 v0, s1, 2, v170
	v_add_u32_e32 v0, 0xa000, v0
	s_waitcnt vmcnt(2)
	v_mfma_f32_16x16x32_bf16 v[188:191], v[104:107], v[12:15], 0
	v_mfma_f32_16x16x32_bf16 v[116:119], v[92:95], v[4:7], 0
	v_mfma_f32_16x16x32_bf16 v[92:95], v[92:95], v[12:15], 0
	s_waitcnt lgkmcnt(1)
	v_mfma_f32_16x16x32_bf16 v[192:195], v[112:115], v[4:7], 0
	v_mfma_f32_16x16x32_bf16 v[196:199], v[112:115], v[12:15], 0
	v_mfma_f32_16x16x32_bf16 v[120:123], v[96:99], v[8:11], v[116:119]
	s_waitcnt vmcnt(1)
	v_mfma_f32_16x16x32_bf16 v[104:107], v[96:99], v[16:19], v[92:95]
	v_mfma_f32_16x16x32_bf16 v[112:115], v[172:175], v[8:11], v[184:187]
	s_nop 4
	v_mfma_f32_16x16x32_bf16 v[96:99], v[172:175], v[16:19], v[188:191]
	ds_read2_b32 v[174:175], v0 offset1:16
	s_waitcnt lgkmcnt(0)
	v_and_b32_e32 v0, s0, v174
	v_mfma_f32_16x16x32_bf16 v[180:183], v[100:103], v[4:7], 0
	v_cmp_eq_u32_e32 vcc, 0, v0
	v_and_b32_e32 v0, s0, v175
	v_mfma_f32_16x16x32_bf16 v[100:103], v[100:103], v[12:15], 0
	v_cndmask_b32_e32 v173, 0, v147, vcc
	v_cmp_eq_u32_e32 vcc, 0, v0
	v_mfma_f32_16x16x32_bf16 v[116:119], v[108:111], v[8:11], v[180:183]
	v_max_f32_e32 v0, v120, v121
	v_max_f32_e32 v2, v122, v123
	v_mfma_f32_16x16x32_bf16 v[100:103], v[108:111], v[16:19], v[100:103]
	v_cndmask_b32_e32 v172, 0, v147, vcc
	s_nop 2
	v_mfma_f32_16x16x32_bf16 v[108:111], v[176:179], v[8:11], v[192:195]
	v_max_f32_e32 v167, v118, v119
	v_max3_f32 v167, v116, v117, v167
	v_max3_f32 v0, v0, v2, v167
	v_max_f32_e32 v2, v114, v115
	s_nop 1
	v_max_f32_e32 v167, v110, v111
	v_max3_f32 v2, v112, v113, v2
	v_max3_f32 v167, v108, v109, v167
	v_max3_f32 v0, v0, v2, v167
	v_max_f32_e32 v2, v104, v105
	v_mfma_f32_16x16x32_bf16 v[92:95], v[176:179], v[16:19], v[196:199]
	v_max_f32_e32 v167, v106, v107
	v_max_f32_e32 v168, v102, v103
	v_max3_f32 v168, v100, v101, v168
	v_max3_f32 v2, v2, v167, v168
	v_max_f32_e32 v167, v98, v99
	v_max_f32_e32 v174, v94, v94
	v_max_f32_e32 v168, v174, v95
	v_max3_f32 v167, v96, v97, v167
	v_max3_f32 v168, v92, v93, v168
	v_max3_f32 v2, v2, v167, v168
	v_mov_b32_e32 v167, v0
	s_nop 1
	v_permlane16_swap_b32_e32 v0, v167
	v_max_f32_e32 v167, v167, v167
	v_max_f32_e32 v0, v0, v0
	v_max_f32_e32 v0, v0, v167
	v_mov_b32_e32 v167, v2
	s_nop 1
	v_permlane16_swap_b32_e32 v2, v167
	v_max_f32_e32 v167, v167, v167
	v_max_f32_e32 v2, v2, v2
	v_max_f32_e32 v2, v2, v167
	v_mov_b32_e32 v167, v0
	s_nop 1
	v_permlane32_swap_b32_e32 v0, v167
	v_max_f32_e32 v167, v167, v167
	v_max_f32_e32 v0, v0, v0
	v_max_f32_e32 v0, v0, v167
	v_mov_b32_e32 v167, v2
	s_nop 1
	v_permlane32_swap_b32_e32 v2, v167
	v_max_f32_e32 v167, v167, v167
	v_max_f32_e32 v2, v2, v2
	v_max_f32_e32 v2, v2, v167
	v_fmamk_f32 v0, v0, 0x3fb8aa3b, v173
	v_fmamk_f32 v2, v2, 0x3fb8aa3b, v172
	v_max_f32_e32 v0, v166, v0
	v_max_f32_e32 v2, v165, v2
	v_sub_f32_e32 v167, v0, v166
	v_sub_f32_e32 v168, v2, v165
	v_max_f32_e32 v167, v167, v168
	v_cmp_lt_f32_e32 vcc, s16, v167
	s_cmp_eq_u64 vcc, 0
	s_cselect_b64 vcc, -1, 0
	v_cndmask_b32_e32 v167, v0, v166, vcc
	v_cndmask_b32_e32 v168, v2, v165, vcc
	v_sub_f32_e32 v0, v166, v167
	v_exp_f32_e32 v2, v0
	v_sub_f32_e32 v0, v165, v168
	v_exp_f32_e32 v0, v0
	v_cmp_neq_f32_e32 vcc, 1.0, v2
	v_cmp_neq_f32_e64 s[0:1], 1.0, v0
	s_or_b64 vcc, vcc, s[0:1]
	s_cbranch_vccz .LBB0_654
	v_pk_mul_f32 v[82:83], v[82:83], v[2:3] op_sel_hi:[1,0]
	v_pk_mul_f32 v[80:81], v[80:81], v[2:3] op_sel_hi:[1,0]
	v_pk_mul_f32 v[74:75], v[74:75], v[2:3] op_sel_hi:[1,0]
	v_pk_mul_f32 v[72:73], v[72:73], v[2:3] op_sel_hi:[1,0]
	v_pk_mul_f32 v[66:67], v[66:67], v[2:3] op_sel_hi:[1,0]
	v_pk_mul_f32 v[64:65], v[64:65], v[2:3] op_sel_hi:[1,0]
	v_pk_mul_f32 v[58:59], v[58:59], v[2:3] op_sel_hi:[1,0]
	v_pk_mul_f32 v[56:57], v[56:57], v[2:3] op_sel_hi:[1,0]
	v_pk_mul_f32 v[78:79], v[78:79], v[0:1] op_sel_hi:[1,0]
	v_pk_mul_f32 v[76:77], v[76:77], v[0:1] op_sel_hi:[1,0]
	v_pk_mul_f32 v[70:71], v[70:71], v[0:1] op_sel_hi:[1,0]
	v_pk_mul_f32 v[68:69], v[68:69], v[0:1] op_sel_hi:[1,0]
	v_pk_mul_f32 v[62:63], v[62:63], v[0:1] op_sel_hi:[1,0]
	v_pk_mul_f32 v[60:61], v[60:61], v[0:1] op_sel_hi:[1,0]
	v_pk_mul_f32 v[54:55], v[54:55], v[0:1] op_sel_hi:[1,0]
	v_pk_mul_f32 v[52:53], v[52:53], v[0:1] op_sel_hi:[1,0]
	v_pk_mul_f32 v[86:87], v[86:87], v[2:3] op_sel_hi:[1,0]
	v_pk_mul_f32 v[84:85], v[84:85], v[2:3] op_sel_hi:[1,0]
	v_pk_mul_f32 v[90:91], v[90:91], v[0:1] op_sel_hi:[1,0]
	v_pk_mul_f32 v[88:89], v[88:89], v[0:1] op_sel_hi:[1,0]

; DEVI void attn_item(const Params& p, int bg, int t0, unsigned char* smem) {
;     ...
;     auto tile_ptrs = [&](int n, const bf16_t*& kp, const bf16_t*& vp) {
;         if (n < n2) { const int c = n < n1 ? n : n - n1; kp = kc + (size_t)c * 4096; vp = vct + (size_t)c * 4096; }
;         else if (n < n3) { const int j = n - n2; kp = ksl + (size_t)j * 4096; vp = vsl + (size_t)j * 4096; }
;         else { const int j = jlo + (n - n3); kp = kwn + (size_t)j * 4096; vp = vwn + (size_t)j * 4096; }
;     ...
;     auto body = [&](auto kc, const int n) {
;         constexpr int KIND = decltype(kc)::value;
;         asm volatile("s_waitcnt vmcnt(0)\n\ts_barrier" ::: "memory");
;         if (n + 1 < ntot) {
;             const bf16_t *kp, *vp; tile_ptrs(n + 1, kp, vp);
;             glds_tile4(gv0, gv1, kp, vp, __builtin_amdgcn_readfirstlane(alds0 + ((n + 1) & 1) * 16384));
.LBB0_687:
	s_mov_b32 s17, s90
	s_add_i32 s90, s90, 1
	s_cmp_ge_i32 s90, s22
	s_cselect_b64 s[38:39], -1, 0
	s_and_b64 vcc, exec, s[38:39]
	s_cbranch_vccnz .Lawb_h
	s_add_i32 s1, s88, 2
	s_cmp_ge_u32 s90, s80
	s_mov_b64 s[68:69], -1
	s_cbranch_scc0 .LBB0_694
	s_cmp_ge_i32 s90, s81
	s_mov_b64 s[14:15], -1
	s_cbranch_scc0 .LBB0_691
	s_add_i32 s0, s10, s17
	s_mov_b64 s[14:15], 0

; DEVI f32x4 mfma16(bf16x8 a, bf16x8 b, f32x4 c) { return __builtin_amdgcn_mfma_f32_16x16x32_bf16(a, b, c, 0, 0, 0); }
; DEVI void attn_item(const Params& p, int bg, int t0, unsigned char* smem) {
;     ...
;             f32x4 s[2][4];
;             {
;                 bf16x8 k0[4], k1[4];
; #pragma unroll
;                 for (int mt = 0; mt < 4; ++mt) {
;                     k0[mt] = *(const bf16x8*)(cK + (mt * 16 + l16) * 128 + ((quad ^ rsw) * 16));
;                     k1[mt] = *(const bf16x8*)(cK + (mt * 16 + l16) * 128 + (((4 + quad) ^ rsw) * 16));
;                 }
; #pragma unroll
;                 for (int mt = 0; mt < 4; ++mt)
; #pragma unroll
;                     for (int ct = 0; ct < 2; ++ct) s[ct][mt] = mfma16(k0[mt], qf[ct][0], (f32x4){0.f, 0.f, 0.f, 0.f});
; #pragma unroll
;                 for (int mt = 0; mt < 4; ++mt)
; #pragma unroll
;                     for (int ct = 0; ct < 2; ++ct) s[ct][mt] = mfma16(k1[mt], qf[ct][1], s[ct][mt]);
;     ...
;                     if (elem) {
; #pragma unroll
;                         for (int ct = 0; ct < 2; ++ct) {
;                             mr[ct] = NINF;
; #pragma unroll
;                             for (int mt = 0; mt < 4; ++mt)
; #pragma unroll
;                                 for (int rr = 0; rr < 4; ++rr) {
;                                     float x = __builtin_fmaf(s[ct][mt][rr], LOG2E, bias[ct]);
;                                     const int dist = tq[ct] - (jt * 64 + mt * 16 + quad * 4 + rr);
;                                     x = (dist >= 0 && dist < wlim) ? x : NINF;
;                                     s[ct][mt][rr] = x; mr[ct] = fmaxf(mr[ct], x);
;                                 }
.Lawb_h:
	s_waitcnt vmcnt(0)
	s_barrier
.LBB0_697:
	s_addk_i32 s70, 0x4000
	s_and_b32 s0, s70, 0x4000
	v_or_b32_e32 v3, s0, v160
	v_add_u32_e32 v0, v3, v161
	ds_read_b128 v[168:171], v0
	v_add_u32_e32 v2, v3, v162
	ds_read_b128 v[172:175], v2
	ds_read_b128 v[176:179], v0 offset:2048
	ds_read_b128 v[180:183], v2 offset:2048
	ds_read_b128 v[184:187], v0 offset:4096
	ds_read_b128 v[188:191], v2 offset:4096
	ds_read_b128 v[192:195], v0 offset:6144
	ds_read_b128 v[196:199], v2 offset:6144
	s_waitcnt lgkmcnt(5)
	v_mfma_f32_16x16x32_bf16 v[204:207], v[176:179], v[4:7], 0
	v_add_u32_e32 v2, s11, v73
	v_add_u32_e32 v74, 19, v2
	v_cmp_gt_u32_e32 vcc, s76, v74
	v_mfma_f32_16x16x32_bf16 v[176:179], v[176:179], v[12:15], 0
	v_add_u32_e32 v74, 18, v2
	v_add_u32_e32 v75, 17, v2
	v_mfma_f32_16x16x32_bf16 v[200:203], v[168:171], v[4:7], 0
	v_mfma_f32_16x16x32_bf16 v[168:171], v[168:171], v[12:15], 0
	v_mfma_f32_16x16x32_bf16 v[200:203], v[172:175], v[8:11], v[200:203]
	s_waitcnt lgkmcnt(3)
	v_mfma_f32_16x16x32_bf16 v[208:211], v[184:187], v[4:7], 0
	v_mfma_f32_16x16x32_bf16 v[216:219], v[172:175], v[16:19], v[168:171]
	s_nop 4
	v_fma_f32 v0, v200, s77, 0
	v_cndmask_b32_e32 v134, v147, v0, vcc
	v_fma_f32 v0, v201, s77, 0
	v_mfma_f32_16x16x32_bf16 v[170:173], v[180:183], v[8:11], v[204:207]
	v_cmp_gt_u32_e32 vcc, s76, v74
	v_fma_f32 v74, v202, s77, 0
	s_nop 0
	v_cndmask_b32_e32 v163, v147, v0, vcc
	v_cmp_gt_u32_e32 vcc, s76, v75
	v_add_u32_e32 v75, 16, v2
	s_waitcnt lgkmcnt(1)
	v_mfma_f32_16x16x32_bf16 v[212:215], v[192:195], v[4:7], 0
	v_cndmask_b32_e32 v167, v147, v74, vcc
	v_fma_f32 v74, v203, s77, 0
	v_cmp_gt_u32_e32 vcc, s76, v75
	v_add_u32_e32 v75, 3, v2
	v_mfma_f32_16x16x32_bf16 v[204:207], v[180:183], v[16:19], v[176:179]
	v_cndmask_b32_e32 v168, v147, v74, vcc
	v_fma_f32 v74, v170, s77, 0
	v_cmp_gt_u32_e32 vcc, s76, v75
	v_mfma_f32_16x16x32_bf16 v[174:177], v[188:191], v[8:11], v[208:211]
	v_add_u32_e32 v75, 2, v2
	v_cndmask_b32_e32 v169, v147, v74, vcc
	v_fma_f32 v74, v171, s77, 0
	v_cmp_gt_u32_e32 vcc, s76, v75
	v_add_u32_e32 v75, 1, v2
	s_waitcnt lgkmcnt(0)
; DEVI float fast_exp2(float x) { return __builtin_amdgcn_exp2f(x); }
; DEVI void attn_item(const Params& p, int bg, int t0, unsigned char* smem) {
;     ...
;                         }
; #pragma unroll
;                         for (int ct = 0; ct < 2; ++ct) mr[ct] = rmax16(mr[ct]);
; #pragma unroll
;                         for (int ct = 0; ct < 2; ++ct) mr[ct] = rmax32(mr[ct]);
;                         bool need = false;
; #pragma unroll
;                         for (int ct = 0; ct < 2; ++ct) need = need || (fmaxf(m[ct], mr[ct]) - m[ct] > 8.0f);
;                         const bool resc = __builtin_amdgcn_ballot_w64(need) != 0;
; #pragma unroll
;                         for (int ct = 0; ct < 2; ++ct) {
;                             mn[ct] = resc ? fmaxf(m[ct], mr[ct]) : m[ct];
; #pragma unroll
;                             for (int mt = 0; mt < 4; ++mt)
; #pragma unroll
;                                 for (int rr = 0; rr < 4; ++rr) { s[ct][mt][rr] = fast_exp2(s[ct][mt][rr] - mn[ct]); }
;                         }
;                     } else {
; #pragma unroll
;                         for (int ct = 0; ct < 2; ++ct) {
;                             mr[ct] = fmaxf(fmaxf(s[ct][0][0], s[ct][0][1]), fmaxf(s[ct][0][2], s[ct][0][3]));
; #pragma unroll
;                             for (int mt = 1; mt < 4; ++mt) mr[ct] = fmaxf(mr[ct], fmaxf(fmaxf(s[ct][mt][0], s[ct][mt][1]), fmaxf(s[ct][mt][2], s[ct][mt][3])));
;                         }
; #pragma unroll
;                         for (int ct = 0; ct < 2; ++ct) mr[ct] = rmax16(mr[ct]);
; #pragma unroll
;                         for (int ct = 0; ct < 2; ++ct) mr[ct] = rmax32(mr[ct]);
;                         float cand[2];
;                         bool need = false;
; #pragma unroll
;                         for (int ct = 0; ct < 2; ++ct) {
;                             cand[ct] = fmaxf(m[ct], __builtin_fmaf(mr[ct], LOG2E, bias[ct]));
;                             need = need || (cand[ct] - m[ct] > 8.0f);
;                         }
;                         const bool resc = __builtin_amdgcn_ballot_w64(need) != 0;
; #pragma unroll
;                         for (int ct = 0; ct < 2; ++ct) {
;                             mn[ct] = resc ? cand[ct] : m[ct];
;                             const float nb = bias[ct] - mn[ct];
; #pragma unroll
;                             for (int mt = 0; mt < 4; ++mt)
; #pragma unroll
	v_mfma_f32_16x16x32_bf16 v[178:181], v[196:199], v[8:11], v[212:215]
	v_cndmask_b32_e32 v170, v147, v74, vcc
	v_fma_f32 v74, v172, s77, 0
	v_cmp_gt_u32_e32 vcc, s76, v75
	v_add_u32_e32 v75, -13, v2
	v_mfma_f32_16x16x32_bf16 v[184:187], v[184:187], v[12:15], 0
	v_cndmask_b32_e32 v171, v147, v74, vcc
	v_fma_f32 v74, v173, s77, 0
	v_cmp_gt_u32_e32 vcc, s76, v2
	v_add_u32_e32 v183, 21, v2
	v_mfma_f32_16x16x32_bf16 v[208:211], v[188:191], v[16:19], v[184:187]
	v_cndmask_b32_e32 v172, v147, v74, vcc
	v_fma_f32 v74, v174, s77, 0
	v_cmp_gt_u32_e32 vcc, s76, v75
	v_add_u32_e32 v75, -14, v2
	v_add_u32_e32 v184, 20, v2
	v_cndmask_b32_e32 v173, v147, v74, vcc
	v_fma_f32 v74, v175, s77, 0
	v_cmp_gt_u32_e32 vcc, s76, v75
	v_add_u32_e32 v75, -15, v2
	v_add_u32_e32 v185, 7, v2
	v_cndmask_b32_e32 v174, v147, v74, vcc
	v_fma_f32 v74, v176, s77, 0
	v_cmp_gt_u32_e32 vcc, s76, v75
	v_add_u32_e32 v75, -16, v2
	v_mfma_f32_16x16x32_bf16 v[192:195], v[192:195], v[12:15], 0
	v_cndmask_b32_e32 v175, v147, v74, vcc
	v_fma_f32 v74, v177, s77, 0
	v_cmp_gt_u32_e32 vcc, s76, v75
	v_subrev_u32_e32 v75, 29, v2
	v_add_u32_e32 v186, 6, v2
	v_cndmask_b32_e32 v176, v147, v74, vcc
	v_fma_f32 v74, v178, s77, 0
	v_cmp_gt_u32_e32 vcc, s76, v75
	v_subrev_u32_e32 v75, 30, v2
	v_add_u32_e32 v187, 5, v2
	v_cndmask_b32_e32 v177, v147, v74, vcc
	v_fma_f32 v74, v179, s77, 0
	v_cmp_gt_u32_e32 vcc, s76, v75
	v_subrev_u32_e32 v75, 31, v2
	v_add_u32_e32 v188, 4, v2
	v_cndmask_b32_e32 v178, v147, v74, vcc
	v_fma_f32 v74, v180, s77, 0
	v_cmp_gt_u32_e32 vcc, s76, v75
	v_subrev_u32_e32 v75, 32, v2
	v_add_u32_e32 v189, -9, v2
	v_cndmask_b32_e32 v179, v147, v74, vcc
	v_fma_f32 v74, v181, s77, 0
	v_cmp_gt_u32_e32 vcc, s76, v75
	v_add_u32_e32 v75, 23, v2
	v_mfma_f32_16x16x32_bf16 v[194:197], v[196:199], v[16:19], v[192:195]
	v_cndmask_b32_e32 v180, v147, v74, vcc
	v_fma_f32 v74, v216, s77, 0
	v_cmp_gt_u32_e32 vcc, s76, v75
	v_add_u32_e32 v75, 22, v2
	v_add_u32_e32 v190, -10, v2
	v_cndmask_b32_e32 v181, v147, v74, vcc
	v_fma_f32 v74, v217, s77, 0
	v_cmp_gt_u32_e32 vcc, s76, v75
	v_fma_f32 v75, v218, s77, 0
	v_max3_f32 v0, v134, s78, v163
	v_cndmask_b32_e32 v182, v147, v74, vcc
	v_cmp_gt_u32_e32 vcc, s76, v183
	v_add_u32_e32 v191, -11, v2
	v_max3_f32 v0, v0, v167, v168
	v_cndmask_b32_e32 v183, v147, v75, vcc
	v_fma_f32 v75, v219, s77, 0
	v_cmp_gt_u32_e32 vcc, s76, v184
	v_max3_f32 v74, v181, s78, v182
	v_add_u32_e32 v192, -12, v2
	v_cndmask_b32_e32 v184, v147, v75, vcc
	v_fma_f32 v75, v204, s77, 0
	v_cmp_gt_u32_e32 vcc, s76, v185
	v_max3_f32 v0, v0, v169, v170
	v_max3_f32 v74, v74, v183, v184
	v_cndmask_b32_e32 v185, v147, v75, vcc
	v_fma_f32 v75, v205, s77, 0
	v_cmp_gt_u32_e32 vcc, s76, v186
	v_subrev_u32_e32 v193, 25, v2
	v_max3_f32 v0, v0, v171, v172
	v_cndmask_b32_e32 v186, v147, v75, vcc
	v_fma_f32 v75, v206, s77, 0
	v_cmp_gt_u32_e32 vcc, s76, v187
	v_max3_f32 v74, v74, v185, v186
	v_max3_f32 v0, v0, v173, v174
	v_cndmask_b32_e32 v187, v147, v75, vcc
	v_fma_f32 v75, v207, s77, 0
	v_cmp_gt_u32_e32 vcc, s76, v188
	v_max3_f32 v0, v0, v175, v176
	v_max3_f32 v0, v0, v177, v178
	v_cndmask_b32_e32 v188, v147, v75, vcc
	v_fma_f32 v75, v208, s77, 0
	v_cmp_gt_u32_e32 vcc, s76, v189
	v_max3_f32 v74, v74, v187, v188
	v_max3_f32 v0, v0, v179, v180
	v_cndmask_b32_e32 v189, v147, v75, vcc
	v_fma_f32 v75, v209, s77, 0
	v_cmp_gt_u32_e32 vcc, s76, v190
	s_nop 1
	v_cndmask_b32_e32 v190, v147, v75, vcc
	v_fma_f32 v75, v210, s77, 0
	v_cmp_gt_u32_e32 vcc, s76, v191
	v_max3_f32 v74, v74, v189, v190
	s_nop 0
	v_cndmask_b32_e32 v191, v147, v75, vcc
	v_fma_f32 v75, v211, s77, 0
	v_cmp_gt_u32_e32 vcc, s76, v192
	s_nop 1
	v_cndmask_b32_e32 v192, v147, v75, vcc
	v_fma_f32 v75, v194, s77, 0
	v_cmp_gt_u32_e32 vcc, s76, v193
	v_subrev_u32_e32 v194, 26, v2
	v_max3_f32 v74, v74, v191, v192
	v_cndmask_b32_e32 v193, v147, v75, vcc
	v_fma_f32 v75, v195, s77, 0
	v_cmp_gt_u32_e32 vcc, s76, v194
	v_subrev_u32_e32 v195, 27, v2
	v_subrev_u32_e32 v2, 28, v2
	v_cndmask_b32_e32 v194, v147, v75, vcc
	v_fma_f32 v75, v196, s77, 0
	v_cmp_gt_u32_e32 vcc, s76, v195
	v_max3_f32 v74, v74, v193, v194
	s_nop 0
	v_cndmask_b32_e32 v195, v147, v75, vcc
	v_fma_f32 v75, v197, s77, 0
	v_cmp_gt_u32_e32 vcc, s76, v2
	s_nop 1
	v_cndmask_b32_e32 v196, v147, v75, vcc
	v_max3_f32 v2, v74, v195, v196
	v_mov_b32_e32 v74, v0
	s_nop 1
	v_permlane16_swap_b32_e32 v0, v74
	v_max_f32_e32 v74, v74, v74
	v_max_f32_e32 v0, v0, v0
	v_max_f32_e32 v0, v0, v74
	v_mov_b32_e32 v74, v2
	s_nop 1
	v_permlane16_swap_b32_e32 v2, v74
	v_max_f32_e32 v74, v74, v74
	v_max_f32_e32 v2, v2, v2
	v_max_f32_e32 v2, v2, v74
	v_mov_b32_e32 v74, v0
	v_mov_b32_e32 v75, v2
	s_nop 0
	v_permlane32_swap_b32_e32 v0, v74
	v_permlane32_swap_b32_e32 v2, v75
	v_max3_f32 v0, v130, v0, v74
	v_max3_f32 v2, v89, v2, v75
	v_sub_f32_e32 v74, v0, v130
	v_sub_f32_e32 v75, v2, v89
	v_max_f32_e32 v74, v74, v75
	v_cmp_lt_f32_e32 vcc, s16, v74
	s_cmp_eq_u64 vcc, 0
	s_cselect_b64 vcc, -1, 0
	v_cndmask_b32_e32 v74, v0, v130, vcc
	v_cndmask_b32_e32 v75, v2, v89, vcc
	v_sub_f32_e32 v0, v130, v74
	v_exp_f32_e32 v2, v0
	v_sub_f32_e32 v0, v89, v75
	v_exp_f32_e32 v0, v0
	v_cmp_neq_f32_e32 vcc, 1.0, v2
	v_cmp_neq_f32_e64 s[0:1], 1.0, v0
	s_or_b64 vcc, vcc, s[0:1]
	s_cbranch_vccz .LBB0_699
	v_pk_mul_f32 v[124:125], v[124:125], v[2:3] op_sel_hi:[1,0]
	v_pk_mul_f32 v[122:123], v[122:123], v[2:3] op_sel_hi:[1,0]
	v_pk_mul_f32 v[116:117], v[116:117], v[2:3] op_sel_hi:[1,0]
	v_pk_mul_f32 v[114:115], v[114:115], v[2:3] op_sel_hi:[1,0]
	v_pk_mul_f32 v[104:105], v[104:105], v[2:3] op_sel_hi:[1,0]
	v_pk_mul_f32 v[102:103], v[102:103], v[2:3] op_sel_hi:[1,0]
	v_pk_mul_f32 v[96:97], v[96:97], v[2:3] op_sel_hi:[1,0]
	v_pk_mul_f32 v[94:95], v[94:95], v[2:3] op_sel_hi:[1,0]
	v_pk_mul_f32 v[112:113], v[112:113], v[0:1] op_sel_hi:[1,0]
	v_pk_mul_f32 v[110:111], v[110:111], v[0:1] op_sel_hi:[1,0]
	v_pk_mul_f32 v[108:109], v[108:109], v[0:1] op_sel_hi:[1,0]
	v_pk_mul_f32 v[106:107], v[106:107], v[0:1] op_sel_hi:[1,0]
	v_pk_mul_f32 v[100:101], v[100:101], v[0:1] op_sel_hi:[1,0]
	v_pk_mul_f32 v[98:99], v[98:99], v[0:1] op_sel_hi:[1,0]
	v_pk_mul_f32 v[92:93], v[92:93], v[0:1] op_sel_hi:[1,0]
	v_pk_mul_f32 v[90:91], v[90:91], v[0:1] op_sel_hi:[1,0]
	v_pk_mul_f32 v[128:129], v[128:129], v[2:3] op_sel_hi:[1,0]
	v_pk_mul_f32 v[126:127], v[126:127], v[2:3] op_sel_hi:[1,0]
	v_pk_mul_f32 v[120:121], v[120:121], v[0:1] op_sel_hi:[1,0]
	v_pk_mul_f32 v[118:119], v[118:119], v[0:1] op_sel_hi:[1,0]
